# gemm_accum_glds loops: LDS stage freed mid-iteration, tile k+2 prefetch, counted vmcnt, no clamped tail loads
# speedup vs baseline: 1.0111x; 1.0111x over previous
.LBB0_21:
	s_mul_hi_i32 s26, s27, 0x66666667
	s_lshr_b32 s28, s26, 31
	s_ashr_i32 s26, s26, 4
	s_add_i32 s30, s26, s28
	s_mul_i32 s26, s30, 40
	v_mov_b32_e32 v2, v208
	s_sub_i32 s36, s27, s26
	s_ashr_i32 s37, s36, 31
	v_ashrrev_i32_e32 v3, 6, v2
	v_lshrrev_b32_e32 v0, 3, v2
	v_bfe_u32 v1, v2, 3, 3
	v_lshlrev_b32_e32 v5, 5, v3
	s_lshl_b64 s[40:41], s[36:37], 18
	v_readlane_b32 s44, v251, 27
	v_bitop3_b32 v4, v0, v2, 7 bitop3:0x28
	v_or_b32_e32 v0, v5, v1
	v_readlane_b32 s45, v251, 28
	s_add_u32 s40, s44, s40
	v_ashrrev_i32_e32 v1, 31, v0
	s_addc_u32 s41, s45, s41
	v_lshlrev_b64 v[0:1], 11, v[0:1]
	v_lshl_add_u64 v[0:1], s[40:41], 0, v[0:1]
	v_lshlrev_b32_e32 v128, 4, v4
	v_lshl_add_u64 v[64:65], v[0:1], 0, v[128:129]
	v_lshrrev_b32_e32 v0, 2, v2
	s_ashr_i32 s31, s30, 31
	v_and_b32_e32 v0, 8, v0
	v_bfe_u32 v1, v2, 3, 2
	s_lshl_b64 s[44:45], s[30:31], 18
	v_or3_b32 v0, v0, v1, v5
	s_add_u32 s44, s24, s44
	v_ashrrev_i32_e32 v1, 31, v0
	s_addc_u32 s45, s25, s45
	v_lshlrev_b64 v[0:1], 11, v[0:1]
	v_lshl_add_u64 v[0:1], s[44:45], 0, v[0:1]
	v_lshlrev_b32_e32 v80, 12, v3
	v_lshl_add_u64 v[66:67], v[0:1], 0, v[128:129]
	v_readfirstlane_b32 s26, v80
	v_or_b32_e32 v0, 0x400, v80
	s_waitcnt lgkmcnt(0)
	s_barrier
	s_mov_b32 m0, s26
	s_mov_b64 s[40:41], 0x4000
	v_readfirstlane_b32 s26, v0
	v_or_b32_e32 v0, 0x800, v80
	global_load_lds_dwordx4 v[64:65], off
	v_lshl_add_u64 v[68:69], v[64:65], 0, s[40:41]
	s_mov_b32 m0, s26
	s_mov_b64 s[40:41], 0x8000
	v_readfirstlane_b32 s26, v0
	v_or_b32_e32 v0, 0xc00, v80
	global_load_lds_dwordx4 v[68:69], off
	v_lshl_add_u64 v[70:71], v[64:65], 0, s[40:41]
	s_mov_b32 m0, s26
	s_mov_b64 s[44:45], 0xc000
	v_readfirstlane_b32 s26, v0
	v_add_u32_e32 v0, 0x4000, v80
	global_load_lds_dwordx4 v[70:71], off
	v_lshl_add_u64 v[72:73], v[64:65], 0, s[44:45]
	s_mov_b32 m0, s26
	v_readfirstlane_b32 s26, v0
	v_add_u32_e32 v0, 0x4400, v80
	global_load_lds_dwordx4 v[72:73], off
	s_mov_b32 m0, s26
	v_readfirstlane_b32 s26, v0
	v_add_u32_e32 v0, 0x4800, v80
	global_load_lds_dwordx4 v[66:67], off
	v_lshl_add_u64 v[74:75], v[66:67], 0, s[40:41]
	s_mov_b32 m0, s26
	s_mov_b64 s[40:41], 0x2000
	v_readfirstlane_b32 s26, v0
	v_add_u32_e32 v0, 0x4c00, v80
	global_load_lds_dwordx4 v[74:75], off
	v_lshl_add_u64 v[76:77], v[66:67], 0, s[40:41]
	s_mov_b32 m0, s26
	s_mov_b64 s[40:41], 0xa000
	v_readfirstlane_b32 s26, v0
	global_load_lds_dwordx4 v[76:77], off
	v_lshl_add_u64 v[78:79], v[66:67], 0, s[40:41]
	s_mov_b32 m0, s26
	v_and_b32_e32 v0, 7, v2
	global_load_lds_dwordx4 v[78:79], off
	v_lshlrev_b32_e32 v1, 7, v2
	v_lshlrev_b32_e32 v0, 4, v0
	v_and_b32_e32 v1, 0x780, v1
	v_bitop3_b32 v0, v0, v2, 48 bitop3:0x78
	v_or_b32_e32 v81, v0, v1
	v_bitop3_b32 v82, v0, 64, v1 bitop3:0x36
	v_lshlrev_b32_e32 v0, 6, v2
	v_and_b32_e32 v83, 0xffffe000, v0
	v_lshlrev_b32_e32 v0, 13, v3
	v_and_b32_e32 v0, 0x2000, v0
	v_or_b32_e32 v84, 0x4000, v0
	v_mov_b32_e32 v0, 0
	s_mov_b32 s26, 64
	s_mov_b32 s31, 0
	v_mov_b32_e32 v1, v0
	v_mov_b32_e32 v2, v0
	v_mov_b32_e32 v3, v0
	v_mov_b32_e32 v4, v0
	v_mov_b32_e32 v5, v0
	v_mov_b32_e32 v6, v0
	v_mov_b32_e32 v7, v0
	v_mov_b32_e32 v8, v0
	v_mov_b32_e32 v9, v0
	v_mov_b32_e32 v10, v0
	v_mov_b32_e32 v11, v0
	v_mov_b32_e32 v12, v0
	v_mov_b32_e32 v13, v0
	v_mov_b32_e32 v14, v0
	v_mov_b32_e32 v15, v0
	v_mov_b32_e32 v16, v0
	v_mov_b32_e32 v17, v0
	v_mov_b32_e32 v18, v0
	v_mov_b32_e32 v19, v0
	v_mov_b32_e32 v20, v0
	v_mov_b32_e32 v21, v0
	v_mov_b32_e32 v22, v0
	v_mov_b32_e32 v23, v0
	v_mov_b32_e32 v24, v0
	v_mov_b32_e32 v25, v0
	v_mov_b32_e32 v26, v0
	v_mov_b32_e32 v27, v0
	v_mov_b32_e32 v28, v0
	v_mov_b32_e32 v29, v0
	v_mov_b32_e32 v30, v0
	v_mov_b32_e32 v31, v0
	v_mov_b32_e32 v32, v0
	v_mov_b32_e32 v33, v0
	v_mov_b32_e32 v34, v0
	v_mov_b32_e32 v35, v0
	v_mov_b32_e32 v36, v0
	v_mov_b32_e32 v37, v0
	v_mov_b32_e32 v38, v0
	v_mov_b32_e32 v39, v0
	v_mov_b32_e32 v40, v0
	v_mov_b32_e32 v41, v0
	v_mov_b32_e32 v42, v0
	v_mov_b32_e32 v43, v0
	v_mov_b32_e32 v44, v0
	v_mov_b32_e32 v45, v0
	v_mov_b32_e32 v46, v0
	v_mov_b32_e32 v47, v0
	v_mov_b32_e32 v48, v0
	v_mov_b32_e32 v49, v0
	v_mov_b32_e32 v50, v0
	v_mov_b32_e32 v51, v0
	v_mov_b32_e32 v52, v0
	v_mov_b32_e32 v53, v0
	v_mov_b32_e32 v54, v0
	v_mov_b32_e32 v55, v0
	v_mov_b32_e32 v56, v0
	v_mov_b32_e32 v57, v0
	v_mov_b32_e32 v58, v0
	v_mov_b32_e32 v59, v0
	v_mov_b32_e32 v60, v0
	v_mov_b32_e32 v61, v0
	v_mov_b32_e32 v62, v0
	v_mov_b32_e32 v63, v0
	s_movk_i32 s40, 0x80
	s_mov_b32 s41, 0
	v_add_u32_e32 v85, 0x8000, v80
	s_nop 1
	v_readfirstlane_b32 s37, v85
	v_add_u32_e32 v88, 0x400, v85
	v_lshl_add_u64 v[86:87], v[64:65], 0, s[40:41]
	s_mov_b32 m0, s37
	v_readfirstlane_b32 s37, v88
	v_add_u32_e32 v88, 0x800, v85
	global_load_lds_dwordx4 v[86:87], off
	v_lshl_add_u64 v[86:87], v[68:69], 0, s[40:41]
	s_mov_b32 m0, s37
	v_readfirstlane_b32 s37, v88
	v_add_u32_e32 v88, 0xc00, v85
	global_load_lds_dwordx4 v[86:87], off
	v_lshl_add_u64 v[86:87], v[70:71], 0, s[40:41]
	s_mov_b32 m0, s37
	v_readfirstlane_b32 s37, v88
	v_add_u32_e32 v88, 0x4000, v85
	global_load_lds_dwordx4 v[86:87], off
	v_lshl_add_u64 v[86:87], v[72:73], 0, s[40:41]
	s_mov_b32 m0, s37
	v_readfirstlane_b32 s37, v88
	v_add_u32_e32 v88, 0x4400, v85
	global_load_lds_dwordx4 v[86:87], off
	v_lshl_add_u64 v[86:87], v[66:67], 0, s[40:41]
	s_mov_b32 m0, s37
	v_readfirstlane_b32 s37, v88
	v_add_u32_e32 v88, 0x4800, v85
	global_load_lds_dwordx4 v[86:87], off
	v_lshl_add_u64 v[86:87], v[74:75], 0, s[40:41]
	s_mov_b32 m0, s37
	v_readfirstlane_b32 s37, v88
	v_add_u32_e32 v85, 0x4c00, v85
	global_load_lds_dwordx4 v[86:87], off
	v_lshl_add_u64 v[86:87], v[76:77], 0, s[40:41]
	s_mov_b32 m0, s37
	v_readfirstlane_b32 s37, v85
	global_load_lds_dwordx4 v[86:87], off
	v_lshl_add_u64 v[86:87], v[78:79], 0, s[40:41]
	s_mov_b32 m0, s37
	s_nop 0
	global_load_lds_dwordx4 v[86:87], off
.LBB0_22:
	s_cmp_lt_i32 s26, 1024
	s_cbranch_scc1 .LgpJ_w8
	s_waitcnt vmcnt(0)
	s_branch .LgpJ_wd
.LgpJ_w8:
	s_waitcnt vmcnt(8)
.LgpJ_wd:
	s_and_b32 s37, s31, 0x8000
	s_waitcnt lgkmcnt(0)
	s_barrier
	v_add_u32_e32 v85, s37, v83
	v_or_b32_e32 v86, s37, v84
	v_add_u32_e32 v126, v85, v81
	v_add_u32_e32 v85, v85, v82
	v_add_u32_e32 v127, v86, v81
	v_add_u32_e32 v128, v86, v82
	ds_read_b128 v[86:89], v126
	ds_read_b128 v[90:93], v126 offset:2048
	ds_read_b128 v[94:97], v126 offset:4096
	ds_read_b128 v[98:101], v126 offset:6144
	ds_read_b128 v[102:105], v127
	ds_read_b128 v[106:109], v127 offset:2048
	ds_read_b128 v[110:113], v127 offset:4096
	ds_read_b128 v[114:117], v127 offset:6144
	ds_read_b128 v[118:121], v85
	ds_read_b128 v[122:125], v85 offset:2048
	ds_read_b128 v[134:137], v85 offset:4096
	ds_read_b128 v[138:141], v85 offset:6144
	ds_read_b128 v[142:145], v128
	ds_read_b128 v[146:149], v128 offset:2048
	ds_read_b128 v[150:153], v128 offset:4096
	ds_read_b128 v[154:157], v128 offset:6144
	s_waitcnt lgkmcnt(8)
	v_mfma_f32_16x16x32_bf16 v[60:63], v[102:105], v[86:89], v[60:63]
	v_mfma_f32_16x16x32_bf16 v[56:59], v[106:109], v[86:89], v[56:59]
	v_mfma_f32_16x16x32_bf16 v[52:55], v[110:113], v[86:89], v[52:55]
	v_mfma_f32_16x16x32_bf16 v[48:51], v[114:117], v[86:89], v[48:51]
	v_mfma_f32_16x16x32_bf16 v[44:47], v[102:105], v[90:93], v[44:47]
	v_mfma_f32_16x16x32_bf16 v[40:43], v[106:109], v[90:93], v[40:43]
	v_mfma_f32_16x16x32_bf16 v[36:39], v[110:113], v[90:93], v[36:39]
	v_mfma_f32_16x16x32_bf16 v[32:35], v[114:117], v[90:93], v[32:35]
	v_mfma_f32_16x16x32_bf16 v[28:31], v[102:105], v[94:97], v[28:31]
	v_mfma_f32_16x16x32_bf16 v[24:27], v[106:109], v[94:97], v[24:27]
	v_mfma_f32_16x16x32_bf16 v[20:23], v[110:113], v[94:97], v[20:23]
	v_mfma_f32_16x16x32_bf16 v[12:15], v[102:105], v[98:101], v[12:15]
	v_mfma_f32_16x16x32_bf16 v[8:11], v[106:109], v[98:101], v[8:11]
	v_mfma_f32_16x16x32_bf16 v[4:7], v[110:113], v[98:101], v[4:7]
	v_mfma_f32_16x16x32_bf16 v[0:3], v[114:117], v[98:101], v[0:3]
	v_mfma_f32_16x16x32_bf16 v[16:19], v[114:117], v[94:97], v[16:19]
	s_waitcnt lgkmcnt(0)
	s_barrier
	s_add_i32 s40, s26, 64
	s_cmp_ge_i32 s40, 1024
	s_cbranch_scc1 .LgpJ_nd
	v_add_u32_e32 v85, s37, v80
	s_ashr_i32 s41, s40, 31
	s_lshl_b64 s[40:41], s[40:41], 1
	v_readfirstlane_b32 s37, v85
	v_add_u32_e32 v88, 0x400, v85
	v_lshl_add_u64 v[86:87], v[64:65], 0, s[40:41]
	s_mov_b32 m0, s37
	v_readfirstlane_b32 s37, v88
	v_add_u32_e32 v88, 0x800, v85
	global_load_lds_dwordx4 v[86:87], off
	v_lshl_add_u64 v[86:87], v[68:69], 0, s[40:41]
	s_mov_b32 m0, s37
	v_readfirstlane_b32 s37, v88
	v_add_u32_e32 v88, 0xc00, v85
	global_load_lds_dwordx4 v[86:87], off
	v_lshl_add_u64 v[86:87], v[70:71], 0, s[40:41]
	s_mov_b32 m0, s37
	v_readfirstlane_b32 s37, v88
	v_add_u32_e32 v88, 0x4000, v85
	global_load_lds_dwordx4 v[86:87], off
	v_lshl_add_u64 v[86:87], v[72:73], 0, s[40:41]
	s_mov_b32 m0, s37
	v_readfirstlane_b32 s37, v88
	v_add_u32_e32 v88, 0x4400, v85
	global_load_lds_dwordx4 v[86:87], off
	v_lshl_add_u64 v[86:87], v[66:67], 0, s[40:41]
	s_mov_b32 m0, s37
	v_readfirstlane_b32 s37, v88
	v_add_u32_e32 v88, 0x4800, v85
	global_load_lds_dwordx4 v[86:87], off
	v_lshl_add_u64 v[86:87], v[74:75], 0, s[40:41]
	s_mov_b32 m0, s37
	v_readfirstlane_b32 s37, v88
	v_add_u32_e32 v85, 0x4c00, v85
	global_load_lds_dwordx4 v[86:87], off
	v_lshl_add_u64 v[86:87], v[76:77], 0, s[40:41]
	s_mov_b32 m0, s37
	v_readfirstlane_b32 s37, v85
	global_load_lds_dwordx4 v[86:87], off
	v_lshl_add_u64 v[86:87], v[78:79], 0, s[40:41]
	s_mov_b32 m0, s37
	s_nop 0
	global_load_lds_dwordx4 v[86:87], off
.LgpJ_nd:
	s_nop 0
	v_mfma_f32_16x16x32_bf16 v[60:63], v[142:145], v[118:121], v[60:63]
	v_mfma_f32_16x16x32_bf16 v[56:59], v[146:149], v[118:121], v[56:59]
	v_mfma_f32_16x16x32_bf16 v[52:55], v[150:153], v[118:121], v[52:55]
	v_mfma_f32_16x16x32_bf16 v[48:51], v[154:157], v[118:121], v[48:51]
	v_mfma_f32_16x16x32_bf16 v[44:47], v[142:145], v[122:125], v[44:47]
	v_mfma_f32_16x16x32_bf16 v[40:43], v[146:149], v[122:125], v[40:43]
	v_mfma_f32_16x16x32_bf16 v[36:39], v[150:153], v[122:125], v[36:39]
	v_mfma_f32_16x16x32_bf16 v[32:35], v[154:157], v[122:125], v[32:35]
	v_mfma_f32_16x16x32_bf16 v[28:31], v[142:145], v[134:137], v[28:31]
	v_mfma_f32_16x16x32_bf16 v[24:27], v[146:149], v[134:137], v[24:27]
	v_mfma_f32_16x16x32_bf16 v[20:23], v[150:153], v[134:137], v[20:23]
	v_mfma_f32_16x16x32_bf16 v[16:19], v[154:157], v[134:137], v[16:19]
	v_mfma_f32_16x16x32_bf16 v[12:15], v[142:145], v[138:141], v[12:15]
	v_mfma_f32_16x16x32_bf16 v[8:11], v[146:149], v[138:141], v[8:11]
	v_mfma_f32_16x16x32_bf16 v[4:7], v[150:153], v[138:141], v[4:7]
	v_mfma_f32_16x16x32_bf16 v[0:3], v[154:157], v[138:141], v[0:3]
	s_add_i32 s26, s26, 64
	s_add_i32 s31, s31, 0x8000
	s_cmp_lg_u32 s31, 0x80000
	s_cbranch_scc1 .LBB0_22
	s_waitcnt vmcnt(0)
	v_mov_b32_e32 v64, v208
	s_waitcnt lgkmcnt(0)
	s_barrier
	v_mov_b32_e32 v65, v208
	v_and_b32_e32 v67, 15, v64
	v_lshrrev_b32_e32 v64, 1, v64
	v_and_b32_e32 v64, 24, v64
	v_max_f32_e32 v60, v60, v60
	v_max_f32_e32 v61, v61, v61
	v_max_f32_e32 v62, v62, v62
	v_max_f32_e32 v63, v63, v63
	v_max_f32_e32 v56, v56, v56
	v_max_f32_e32 v57, v57, v57
	v_max_f32_e32 v58, v58, v58
	v_max_f32_e32 v60, 0, v60
	v_and_or_b32 v68, v65, 64, v64
	v_max_f32_e32 v61, 0, v61
	v_max_f32_e32 v62, 0, v62
	v_max_f32_e32 v63, 0, v63
	v_max_f32_e32 v56, 0, v56
	v_max_f32_e32 v57, 0, v57
	v_max_f32_e32 v64, 0, v58
	v_max_f32_e32 v58, v59, v59
	v_ashrrev_i32_e32 v66, 1, v65
	s_movk_i32 s26, 0xffc0
	v_max_f32_e32 v65, 0, v58
	v_pk_mul_f32 v[58:59], v[60:61], v[60:61]
	v_pk_mul_f32 v[60:61], v[62:63], v[62:63]
	v_pk_mul_f32 v[56:57], v[56:57], v[56:57]
	v_and_or_b32 v66, v66, s26, v67
	v_cvt_pk_bf16_f32 v58, v58, v59
	v_cvt_pk_bf16_f32 v59, v60, v61
	v_cvt_pk_bf16_f32 v60, v56, v57
	v_pk_mul_f32 v[56:57], v[64:65], v[64:65]
	s_lshl_b32 s30, s30, 7
	v_cvt_pk_bf16_f32 v61, v56, v57
	v_lshl_add_u32 v56, s36, 7, v66
	v_ashrrev_i32_e32 v57, 31, v56
	v_lshlrev_b64 v[62:63], 13, v[56:57]
	s_ashr_i32 s31, s30, 31
	v_lshl_add_u64 v[62:63], s[70:71], 0, v[62:63]
	s_lshl_b64 s[30:31], s[30:31], 1
	v_lshl_add_u64 v[62:63], v[62:63], 0, s[30:31]
	v_lshlrev_b32_e32 v128, 1, v68
	v_lshl_add_u64 v[62:63], v[62:63], 0, v[128:129]
	v_max_f32_e32 v48, v48, v48
	global_store_dwordx4 v[62:63], v[58:61], off
	v_max_f32_e32 v52, v52, v52
	v_max_f32_e32 v53, v53, v53
	v_max_f32_e32 v58, 0, v48
	v_max_f32_e32 v48, v49, v49
	v_max_f32_e32 v54, v54, v54
	v_max_f32_e32 v55, v55, v55
	v_max_f32_e32 v59, 0, v48
	v_max_f32_e32 v48, v50, v50
	v_max_f32_e32 v52, 0, v52
	v_max_f32_e32 v53, 0, v53
	v_max_f32_e32 v54, 0, v54
	v_max_f32_e32 v55, 0, v55
	v_max_f32_e32 v60, 0, v48
	v_max_f32_e32 v48, v51, v51
	v_max_f32_e32 v61, 0, v48
	v_pk_mul_f32 v[48:49], v[52:53], v[52:53]
	v_pk_mul_f32 v[50:51], v[54:55], v[54:55]
	v_cvt_pk_bf16_f32 v48, v48, v49
	v_cvt_pk_bf16_f32 v49, v50, v51
	v_pk_mul_f32 v[50:51], v[58:59], v[58:59]
	v_pk_mul_f32 v[52:53], v[60:61], v[60:61]
	v_cvt_pk_bf16_f32 v50, v50, v51
	v_cvt_pk_bf16_f32 v51, v52, v53
	v_max_f32_e32 v40, v40, v40
	global_store_dwordx4 v[62:63], v[48:51], off offset:64
	v_max_f32_e32 v44, v44, v44
	v_max_f32_e32 v45, v45, v45
	v_max_f32_e32 v48, 0, v40
	v_max_f32_e32 v40, v41, v41
	v_max_f32_e32 v46, v46, v46
	v_max_f32_e32 v47, v47, v47
	v_max_f32_e32 v49, 0, v40
	v_max_f32_e32 v40, v42, v42
	v_max_f32_e32 v44, 0, v44
	v_max_f32_e32 v45, 0, v45
	v_max_f32_e32 v46, 0, v46
	v_max_f32_e32 v47, 0, v47
	v_max_f32_e32 v50, 0, v40
	v_max_f32_e32 v40, v43, v43
	v_max_f32_e32 v51, 0, v40
	v_pk_mul_f32 v[40:41], v[44:45], v[44:45]
	v_pk_mul_f32 v[42:43], v[46:47], v[46:47]
	v_cvt_pk_bf16_f32 v40, v40, v41
	v_cvt_pk_bf16_f32 v41, v42, v43
	v_pk_mul_f32 v[42:43], v[48:49], v[48:49]
	v_pk_mul_f32 v[44:45], v[50:51], v[50:51]
	v_cvt_pk_bf16_f32 v42, v42, v43
	v_cvt_pk_bf16_f32 v43, v44, v45
	v_or_b32_e32 v44, 16, v56
	v_ashrrev_i32_e32 v45, 31, v44
	v_lshlrev_b64 v[44:45], 13, v[44:45]
	v_lshl_add_u64 v[44:45], s[70:71], 0, v[44:45]
	v_lshl_add_u64 v[44:45], v[44:45], 0, s[30:31]
	v_lshl_add_u64 v[44:45], v[44:45], 0, v[128:129]
	v_max_f32_e32 v32, v32, v32
	global_store_dwordx4 v[44:45], v[40:43], off
	v_max_f32_e32 v36, v36, v36
	v_max_f32_e32 v37, v37, v37
	v_max_f32_e32 v40, 0, v32
	v_max_f32_e32 v32, v33, v33
	v_max_f32_e32 v38, v38, v38
	v_max_f32_e32 v39, v39, v39
	v_max_f32_e32 v41, 0, v32
	v_max_f32_e32 v32, v34, v34
	v_max_f32_e32 v36, 0, v36
	v_max_f32_e32 v37, 0, v37
	v_max_f32_e32 v38, 0, v38
	v_max_f32_e32 v39, 0, v39
	v_max_f32_e32 v42, 0, v32
	v_max_f32_e32 v32, v35, v35
	v_max_f32_e32 v43, 0, v32
	v_pk_mul_f32 v[32:33], v[36:37], v[36:37]
	v_pk_mul_f32 v[34:35], v[38:39], v[38:39]
	v_cvt_pk_bf16_f32 v32, v32, v33
	v_cvt_pk_bf16_f32 v33, v34, v35
	v_pk_mul_f32 v[34:35], v[40:41], v[40:41]
	v_pk_mul_f32 v[36:37], v[42:43], v[42:43]
	v_cvt_pk_bf16_f32 v34, v34, v35
	v_cvt_pk_bf16_f32 v35, v36, v37
	v_max_f32_e32 v24, v24, v24
	global_store_dwordx4 v[44:45], v[32:35], off offset:64
	v_max_f32_e32 v28, v28, v28
	v_max_f32_e32 v29, v29, v29
	v_max_f32_e32 v32, 0, v24
	v_max_f32_e32 v24, v25, v25
	v_max_f32_e32 v30, v30, v30
	v_max_f32_e32 v31, v31, v31
	v_max_f32_e32 v33, 0, v24
	v_max_f32_e32 v24, v26, v26
	v_max_f32_e32 v28, 0, v28
	v_max_f32_e32 v29, 0, v29
	v_max_f32_e32 v30, 0, v30
	v_max_f32_e32 v31, 0, v31
	v_max_f32_e32 v34, 0, v24
	v_max_f32_e32 v24, v27, v27
	v_max_f32_e32 v35, 0, v24
	v_pk_mul_f32 v[24:25], v[28:29], v[28:29]
	v_pk_mul_f32 v[26:27], v[30:31], v[30:31]
	v_cvt_pk_bf16_f32 v24, v24, v25
	v_cvt_pk_bf16_f32 v25, v26, v27
	v_pk_mul_f32 v[26:27], v[32:33], v[32:33]
	v_pk_mul_f32 v[28:29], v[34:35], v[34:35]
	v_cvt_pk_bf16_f32 v26, v26, v27
	v_cvt_pk_bf16_f32 v27, v28, v29
	v_or_b32_e32 v28, 32, v56
	v_ashrrev_i32_e32 v29, 31, v28
	v_lshlrev_b64 v[28:29], 13, v[28:29]
	v_lshl_add_u64 v[28:29], s[70:71], 0, v[28:29]
	v_lshl_add_u64 v[28:29], v[28:29], 0, s[30:31]
	v_lshl_add_u64 v[28:29], v[28:29], 0, v[128:129]
	v_max_f32_e32 v16, v16, v16
	global_store_dwordx4 v[28:29], v[24:27], off
	v_max_f32_e32 v20, v20, v20
	v_max_f32_e32 v21, v21, v21
	v_max_f32_e32 v24, 0, v16
	v_max_f32_e32 v16, v17, v17
	v_max_f32_e32 v22, v22, v22
	v_max_f32_e32 v23, v23, v23
	v_max_f32_e32 v25, 0, v16
	v_max_f32_e32 v16, v18, v18
	v_max_f32_e32 v20, 0, v20
	v_max_f32_e32 v21, 0, v21
	v_max_f32_e32 v22, 0, v22
	v_max_f32_e32 v23, 0, v23
	v_max_f32_e32 v26, 0, v16
	v_max_f32_e32 v16, v19, v19
	v_max_f32_e32 v27, 0, v16
	v_pk_mul_f32 v[16:17], v[20:21], v[20:21]
	v_pk_mul_f32 v[18:19], v[22:23], v[22:23]
	v_cvt_pk_bf16_f32 v16, v16, v17
	v_cvt_pk_bf16_f32 v17, v18, v19
	v_pk_mul_f32 v[18:19], v[24:25], v[24:25]
	v_pk_mul_f32 v[20:21], v[26:27], v[26:27]
	v_cvt_pk_bf16_f32 v18, v18, v19
	v_cvt_pk_bf16_f32 v19, v20, v21
	v_max_f32_e32 v8, v8, v8
	global_store_dwordx4 v[28:29], v[16:19], off offset:64
	v_max_f32_e32 v12, v12, v12
	v_max_f32_e32 v13, v13, v13
	v_max_f32_e32 v16, 0, v8
	v_max_f32_e32 v8, v9, v9
	v_max_f32_e32 v14, v14, v14
	v_max_f32_e32 v15, v15, v15
	v_max_f32_e32 v17, 0, v8
	v_max_f32_e32 v8, v10, v10
	v_max_f32_e32 v12, 0, v12
	v_max_f32_e32 v13, 0, v13
	v_max_f32_e32 v14, 0, v14
	v_max_f32_e32 v15, 0, v15
	v_max_f32_e32 v18, 0, v8
	v_max_f32_e32 v8, v11, v11
	v_max_f32_e32 v19, 0, v8
	v_pk_mul_f32 v[8:9], v[12:13], v[12:13]
	v_pk_mul_f32 v[10:11], v[14:15], v[14:15]
	v_cvt_pk_bf16_f32 v8, v8, v9
	v_cvt_pk_bf16_f32 v9, v10, v11
	v_pk_mul_f32 v[10:11], v[16:17], v[16:17]
	v_pk_mul_f32 v[12:13], v[18:19], v[18:19]
	v_cvt_pk_bf16_f32 v10, v10, v11
	v_cvt_pk_bf16_f32 v11, v12, v13
	v_or_b32_e32 v12, 48, v56
	v_ashrrev_i32_e32 v13, 31, v12
	v_lshlrev_b64 v[12:13], 13, v[12:13]
	v_lshl_add_u64 v[12:13], s[70:71], 0, v[12:13]
	v_lshl_add_u64 v[12:13], v[12:13], 0, s[30:31]
	v_lshl_add_u64 v[12:13], v[12:13], 0, v[128:129]
	v_max_f32_e32 v0, v0, v0
	global_store_dwordx4 v[12:13], v[8:11], off
	v_max_f32_e32 v4, v4, v4
	v_max_f32_e32 v5, v5, v5
	v_max_f32_e32 v8, 0, v0
	v_max_f32_e32 v0, v1, v1
	v_max_f32_e32 v6, v6, v6
	v_max_f32_e32 v7, v7, v7
	v_max_f32_e32 v9, 0, v0
	v_max_f32_e32 v0, v2, v2
	v_max_f32_e32 v4, 0, v4
	v_max_f32_e32 v5, 0, v5
	v_max_f32_e32 v6, 0, v6
	v_max_f32_e32 v7, 0, v7
	v_max_f32_e32 v10, 0, v0
	v_max_f32_e32 v0, v3, v3
	v_max_f32_e32 v11, 0, v0
	v_pk_mul_f32 v[0:1], v[4:5], v[4:5]
	v_pk_mul_f32 v[2:3], v[6:7], v[6:7]
	v_cvt_pk_bf16_f32 v0, v0, v1
	v_cvt_pk_bf16_f32 v1, v2, v3
	v_pk_mul_f32 v[2:3], v[8:9], v[8:9]
	v_pk_mul_f32 v[4:5], v[10:11], v[10:11]
	s_add_i32 s27, s27, s22
	v_cvt_pk_bf16_f32 v2, v2, v3
	v_cvt_pk_bf16_f32 v3, v4, v5
	s_cmpk_gt_i32 s27, 0x4ff
	global_store_dwordx4 v[12:13], v[0:3], off offset:64
	s_cbranch_scc0 .LBB0_21

.LBB0_148:
	s_and_b64 vcc, exec, s[0:1]
	s_cbranch_vccz .LBB0_152
	s_add_i32 s0, s27, 0xffc0
	s_and_b32 s1, s0, 0xff
	s_mulk_i32 s1, 0xcd
	s_bfe_u32 s1, s1, 0x3000d
	s_mul_i32 s24, s1, 40
	v_mov_b32_e32 v2, v208
	s_sub_i32 s0, s0, s24
	s_and_b32 s0, s0, 0xff
	v_ashrrev_i32_e32 v3, 6, v2
	v_lshrrev_b32_e32 v0, 3, v2
	v_bfe_u32 v1, v2, 3, 3
	v_lshlrev_b32_e32 v5, 5, v3
	s_add_i32 s26, s1, 51
	s_lshl_b32 s1, s0, 18
	v_readlane_b32 s24, v251, 27
	v_bitop3_b32 v4, v0, v2, 7 bitop3:0x28
	v_or_b32_e32 v0, v5, v1
	v_readlane_b32 s25, v251, 28
	s_add_u32 s24, s24, s1
	v_ashrrev_i32_e32 v1, 31, v0
	s_addc_u32 s25, s25, 0
	v_lshlrev_b64 v[0:1], 11, v[0:1]
	v_lshl_add_u64 v[0:1], s[24:25], 0, v[0:1]
	v_lshlrev_b32_e32 v128, 4, v4
	v_lshl_add_u64 v[64:65], v[0:1], 0, v[128:129]
	v_lshrrev_b32_e32 v0, 2, v2
	v_and_b32_e32 v0, 8, v0
	v_bfe_u32 v1, v2, 3, 2
	s_and_b32 s1, s26, 63
	s_lshl_b32 s26, s26, 18
	v_readlane_b32 s28, v255, 46
	v_or3_b32 v0, v0, v1, v5
	s_add_u32 s30, s28, s26
	v_readlane_b32 s26, v255, 47
	v_ashrrev_i32_e32 v1, 31, v0
	s_addc_u32 s31, s26, 0
	v_lshlrev_b64 v[0:1], 11, v[0:1]
	v_lshlrev_b32_e32 v85, 12, v3
	v_lshl_add_u64 v[0:1], s[30:31], 0, v[0:1]
	v_readfirstlane_b32 s24, v85
	v_lshl_add_u64 v[66:67], v[0:1], 0, v[128:129]
	s_mov_b32 m0, s24
	s_mov_b64 s[24:25], 0x4000
	v_or_b32_e32 v0, 0x400, v85
	s_waitcnt lgkmcnt(0)
	s_barrier
	v_lshl_add_u64 v[68:69], v[64:65], 0, s[24:25]
	v_readfirstlane_b32 s24, v0
	v_or_b32_e32 v0, 0x800, v85
	global_load_lds_dwordx4 v[64:65], off
	s_mov_b32 m0, s24
	v_readfirstlane_b32 s24, v0
	global_load_lds_dwordx4 v[68:69], off
	s_mov_b64 s[30:31], 0x8000
	s_mov_b32 m0, s24
	s_mov_b64 s[24:25], 0xc000
	v_or_b32_e32 v0, 0xc00, v85
	v_lshl_add_u64 v[70:71], v[64:65], 0, s[30:31]
	v_lshl_add_u64 v[72:73], v[64:65], 0, s[24:25]
	v_readfirstlane_b32 s24, v0
	v_add_u32_e32 v0, 0x4000, v85
	global_load_lds_dwordx4 v[70:71], off
	s_mov_b32 m0, s24
	v_readfirstlane_b32 s24, v0
	v_add_u32_e32 v0, 0x4400, v85
	global_load_lds_dwordx4 v[72:73], off
	s_mov_b32 m0, s24
	v_readfirstlane_b32 s24, v0
	global_load_lds_dwordx4 v[66:67], off
	s_mov_b32 m0, s24
	s_mov_b64 s[24:25], 0x2000
	v_add_u32_e32 v0, 0x4800, v85
	v_lshl_add_u64 v[74:75], v[66:67], 0, s[30:31]
	v_lshl_add_u64 v[76:77], v[66:67], 0, s[24:25]
	v_readfirstlane_b32 s24, v0
	global_load_lds_dwordx4 v[74:75], off
	s_mov_b32 m0, s24
	s_mov_b64 s[24:25], 0xa000
	v_add_u32_e32 v0, 0x4c00, v85
	v_lshl_add_u64 v[78:79], v[66:67], 0, s[24:25]
	v_readfirstlane_b32 s24, v0
	global_load_lds_dwordx4 v[76:77], off
	s_mov_b32 m0, s24
	v_and_b32_e32 v0, 7, v2
	global_load_lds_dwordx4 v[78:79], off
	v_lshlrev_b32_e32 v1, 7, v2
	v_lshlrev_b32_e32 v0, 4, v0
	v_and_b32_e32 v1, 0x780, v1
	v_bitop3_b32 v0, v0, v2, 48 bitop3:0x78
	v_or_b32_e32 v86, v0, v1
	v_bitop3_b32 v87, v0, 64, v1 bitop3:0x36
	v_lshlrev_b32_e32 v0, 6, v2
	v_and_b32_e32 v88, 0xffffe000, v0
	v_lshlrev_b32_e32 v0, 13, v3
	v_and_b32_e32 v0, 0x2000, v0
	v_or_b32_e32 v89, 0x4000, v0
	v_mov_b32_e32 v0, 0
	s_mov_b32 s24, 64
	s_mov_b32 s26, 0
	v_mov_b32_e32 v1, v0
	v_mov_b32_e32 v2, v0
	v_mov_b32_e32 v3, v0
	v_mov_b32_e32 v4, v0
	v_mov_b32_e32 v5, v0
	v_mov_b32_e32 v6, v0
	v_mov_b32_e32 v7, v0
	v_mov_b32_e32 v8, v0
	v_mov_b32_e32 v9, v0
	v_mov_b32_e32 v10, v0
	v_mov_b32_e32 v11, v0
	v_mov_b32_e32 v12, v0
	v_mov_b32_e32 v13, v0
	v_mov_b32_e32 v14, v0
	v_mov_b32_e32 v15, v0
	v_mov_b32_e32 v16, v0
	v_mov_b32_e32 v17, v0
	v_mov_b32_e32 v18, v0
	v_mov_b32_e32 v19, v0
	v_mov_b32_e32 v20, v0
	v_mov_b32_e32 v21, v0
	v_mov_b32_e32 v22, v0
	v_mov_b32_e32 v23, v0
	v_mov_b32_e32 v24, v0
	v_mov_b32_e32 v25, v0
	v_mov_b32_e32 v26, v0
	v_mov_b32_e32 v27, v0
	v_mov_b32_e32 v28, v0
	v_mov_b32_e32 v29, v0
	v_mov_b32_e32 v30, v0
	v_mov_b32_e32 v31, v0
	v_mov_b32_e32 v32, v0
	v_mov_b32_e32 v33, v0
	v_mov_b32_e32 v34, v0
	v_mov_b32_e32 v35, v0
	v_mov_b32_e32 v36, v0
	v_mov_b32_e32 v37, v0
	v_mov_b32_e32 v38, v0
	v_mov_b32_e32 v39, v0
	v_mov_b32_e32 v40, v0
	v_mov_b32_e32 v41, v0
	v_mov_b32_e32 v42, v0
	v_mov_b32_e32 v43, v0
	v_mov_b32_e32 v44, v0
	v_mov_b32_e32 v45, v0
	v_mov_b32_e32 v46, v0
	v_mov_b32_e32 v47, v0
	v_mov_b32_e32 v48, v0
	v_mov_b32_e32 v49, v0
	v_mov_b32_e32 v50, v0
	v_mov_b32_e32 v51, v0
	v_mov_b32_e32 v52, v0
	v_mov_b32_e32 v53, v0
	v_mov_b32_e32 v54, v0
	v_mov_b32_e32 v55, v0
	v_mov_b32_e32 v56, v0
	v_mov_b32_e32 v57, v0
	v_mov_b32_e32 v58, v0
	v_mov_b32_e32 v59, v0
	v_mov_b32_e32 v60, v0
	v_mov_b32_e32 v61, v0
	v_mov_b32_e32 v62, v0
	v_mov_b32_e32 v63, v0
	s_movk_i32 s30, 0x80
	s_mov_b32 s31, 0
	v_add_u32_e32 v92, 0x8000, v85
	s_nop 1
	v_readfirstlane_b32 s28, v92
	v_add_u32_e32 v93, 0x400, v92
	v_lshl_add_u64 v[90:91], v[64:65], 0, s[30:31]
	s_mov_b32 m0, s28
	v_readfirstlane_b32 s28, v93
	v_add_u32_e32 v93, 0x800, v92
	global_load_lds_dwordx4 v[90:91], off
	v_lshl_add_u64 v[90:91], v[68:69], 0, s[30:31]
	s_mov_b32 m0, s28
	v_readfirstlane_b32 s28, v93
	v_add_u32_e32 v93, 0xc00, v92
	global_load_lds_dwordx4 v[90:91], off
	v_lshl_add_u64 v[90:91], v[70:71], 0, s[30:31]
	s_mov_b32 m0, s28
	v_readfirstlane_b32 s28, v93
	v_add_u32_e32 v93, 0x4000, v92
	global_load_lds_dwordx4 v[90:91], off
	v_lshl_add_u64 v[90:91], v[72:73], 0, s[30:31]
	s_mov_b32 m0, s28
	v_readfirstlane_b32 s28, v93
	v_add_u32_e32 v93, 0x4400, v92
	global_load_lds_dwordx4 v[90:91], off
	v_lshl_add_u64 v[90:91], v[66:67], 0, s[30:31]
	s_mov_b32 m0, s28
	v_readfirstlane_b32 s28, v93
	v_add_u32_e32 v93, 0x4800, v92
	global_load_lds_dwordx4 v[90:91], off
	v_lshl_add_u64 v[90:91], v[74:75], 0, s[30:31]
	s_mov_b32 m0, s28
	v_readfirstlane_b32 s28, v93
	v_add_u32_e32 v92, 0x4c00, v92
	global_load_lds_dwordx4 v[90:91], off
	v_lshl_add_u64 v[90:91], v[76:77], 0, s[30:31]
	s_mov_b32 m0, s28
	v_readfirstlane_b32 s28, v92
	global_load_lds_dwordx4 v[90:91], off
	v_lshl_add_u64 v[90:91], v[78:79], 0, s[30:31]
	s_mov_b32 m0, s28
	s_nop 0
	global_load_lds_dwordx4 v[90:91], off
.LBB0_150:
	s_cmp_lt_i32 s24, 1024
	s_cbranch_scc1 .LgpE_w8
	s_waitcnt vmcnt(0)
	s_branch .LgpE_wd

.LgpE_wd:
	s_and_b32 s28, s26, 0x8000
	s_waitcnt lgkmcnt(0)
	s_barrier
	v_add_u32_e32 v90, s28, v88
	v_add_u32_e32 v126, v90, v86
	v_add_u32_e32 v127, v90, v87
	v_or_b32_e32 v90, s28, v89
	v_add_u32_e32 v128, v90, v86
	v_add_u32_e32 v133, v90, v87
	ds_read_b128 v[90:93], v126
	ds_read_b128 v[94:97], v126 offset:2048
	ds_read_b128 v[98:101], v126 offset:4096
	ds_read_b128 v[102:105], v126 offset:6144
	ds_read_b128 v[106:109], v128
	ds_read_b128 v[110:113], v128 offset:2048
	ds_read_b128 v[114:117], v128 offset:4096
	ds_read_b128 v[118:121], v128 offset:6144
	ds_read_b128 v[122:125], v127
	ds_read_b128 v[134:137], v127 offset:2048
	ds_read_b128 v[138:141], v127 offset:4096
	ds_read_b128 v[142:145], v127 offset:6144
	ds_read_b128 v[146:149], v133
	ds_read_b128 v[150:153], v133 offset:2048
	ds_read_b128 v[154:157], v133 offset:4096
	ds_read_b128 v[158:161], v133 offset:6144
	s_waitcnt lgkmcnt(8)
	v_mfma_f32_16x16x32_bf16 v[60:63], v[106:109], v[90:93], v[60:63]
	v_mfma_f32_16x16x32_bf16 v[56:59], v[110:113], v[90:93], v[56:59]
	v_mfma_f32_16x16x32_bf16 v[52:55], v[114:117], v[90:93], v[52:55]
	v_mfma_f32_16x16x32_bf16 v[48:51], v[118:121], v[90:93], v[48:51]
	v_mfma_f32_16x16x32_bf16 v[44:47], v[106:109], v[94:97], v[44:47]
	v_mfma_f32_16x16x32_bf16 v[40:43], v[110:113], v[94:97], v[40:43]
	v_mfma_f32_16x16x32_bf16 v[36:39], v[114:117], v[94:97], v[36:39]
	v_mfma_f32_16x16x32_bf16 v[32:35], v[118:121], v[94:97], v[32:35]
	v_mfma_f32_16x16x32_bf16 v[28:31], v[106:109], v[98:101], v[28:31]
	v_mfma_f32_16x16x32_bf16 v[24:27], v[110:113], v[98:101], v[24:27]
	v_mfma_f32_16x16x32_bf16 v[20:23], v[114:117], v[98:101], v[20:23]
	v_mfma_f32_16x16x32_bf16 v[12:15], v[106:109], v[102:105], v[12:15]
	v_mfma_f32_16x16x32_bf16 v[8:11], v[110:113], v[102:105], v[8:11]
	v_mfma_f32_16x16x32_bf16 v[4:7], v[114:117], v[102:105], v[4:7]
	v_mfma_f32_16x16x32_bf16 v[0:3], v[118:121], v[102:105], v[0:3]
	v_mfma_f32_16x16x32_bf16 v[16:19], v[118:121], v[98:101], v[16:19]
	s_waitcnt lgkmcnt(0)
	s_barrier
	s_add_i32 s30, s24, 64
	s_cmp_ge_i32 s30, 1024
	s_cbranch_scc1 .LgpE_nd
	v_add_u32_e32 v92, s28, v85
	s_ashr_i32 s31, s30, 31
	s_lshl_b64 s[30:31], s[30:31], 1
	v_readfirstlane_b32 s28, v92
	v_add_u32_e32 v93, 0x400, v92
	v_lshl_add_u64 v[90:91], v[64:65], 0, s[30:31]
	s_mov_b32 m0, s28
	v_readfirstlane_b32 s28, v93
	v_add_u32_e32 v93, 0x800, v92
	global_load_lds_dwordx4 v[90:91], off
	v_lshl_add_u64 v[90:91], v[68:69], 0, s[30:31]
	s_mov_b32 m0, s28
	v_readfirstlane_b32 s28, v93
	v_add_u32_e32 v93, 0xc00, v92
	global_load_lds_dwordx4 v[90:91], off
	v_lshl_add_u64 v[90:91], v[70:71], 0, s[30:31]
	s_mov_b32 m0, s28
	v_readfirstlane_b32 s28, v93
	v_add_u32_e32 v93, 0x4000, v92
	global_load_lds_dwordx4 v[90:91], off
	v_lshl_add_u64 v[90:91], v[72:73], 0, s[30:31]
	s_mov_b32 m0, s28
	v_readfirstlane_b32 s28, v93
	v_add_u32_e32 v93, 0x4400, v92
	global_load_lds_dwordx4 v[90:91], off
	v_lshl_add_u64 v[90:91], v[66:67], 0, s[30:31]
	s_mov_b32 m0, s28
	v_readfirstlane_b32 s28, v93
	v_add_u32_e32 v93, 0x4800, v92
	global_load_lds_dwordx4 v[90:91], off
	v_lshl_add_u64 v[90:91], v[74:75], 0, s[30:31]
	s_mov_b32 m0, s28
	v_readfirstlane_b32 s28, v93
	v_add_u32_e32 v92, 0x4c00, v92
	global_load_lds_dwordx4 v[90:91], off
	v_lshl_add_u64 v[90:91], v[76:77], 0, s[30:31]
	s_mov_b32 m0, s28
	v_readfirstlane_b32 s28, v92
	global_load_lds_dwordx4 v[90:91], off
	v_lshl_add_u64 v[90:91], v[78:79], 0, s[30:31]
	s_mov_b32 m0, s28
	s_nop 0
	global_load_lds_dwordx4 v[90:91], off
.LgpE_nd:
	s_nop 0
	v_mfma_f32_16x16x32_bf16 v[60:63], v[146:149], v[122:125], v[60:63]
	v_mfma_f32_16x16x32_bf16 v[56:59], v[150:153], v[122:125], v[56:59]
	v_mfma_f32_16x16x32_bf16 v[52:55], v[154:157], v[122:125], v[52:55]
	v_mfma_f32_16x16x32_bf16 v[48:51], v[158:161], v[122:125], v[48:51]
	v_mfma_f32_16x16x32_bf16 v[44:47], v[146:149], v[134:137], v[44:47]
	v_mfma_f32_16x16x32_bf16 v[40:43], v[150:153], v[134:137], v[40:43]
	v_mfma_f32_16x16x32_bf16 v[36:39], v[154:157], v[134:137], v[36:39]
	v_mfma_f32_16x16x32_bf16 v[32:35], v[158:161], v[134:137], v[32:35]
	v_mfma_f32_16x16x32_bf16 v[28:31], v[146:149], v[138:141], v[28:31]
	v_mfma_f32_16x16x32_bf16 v[24:27], v[150:153], v[138:141], v[24:27]
	v_mfma_f32_16x16x32_bf16 v[20:23], v[154:157], v[138:141], v[20:23]
	v_mfma_f32_16x16x32_bf16 v[16:19], v[158:161], v[138:141], v[16:19]
	v_mfma_f32_16x16x32_bf16 v[12:15], v[146:149], v[142:145], v[12:15]
	v_mfma_f32_16x16x32_bf16 v[8:11], v[150:153], v[142:145], v[8:11]
	v_mfma_f32_16x16x32_bf16 v[4:7], v[154:157], v[142:145], v[4:7]
	v_mfma_f32_16x16x32_bf16 v[0:3], v[158:161], v[142:145], v[0:3]
	s_add_i32 s24, s24, 64
	s_add_i32 s26, s26, 0x8000
	s_cmp_lg_u32 s26, 0x80000
	s_cbranch_scc1 .LBB0_150
	s_waitcnt vmcnt(0)
	v_mov_b32_e32 v64, v208
	s_waitcnt lgkmcnt(0)
	s_barrier
	v_mov_b32_e32 v65, v208
	v_and_b32_e32 v67, 15, v64
	v_lshrrev_b32_e32 v64, 1, v64
	v_and_b32_e32 v64, 24, v64
	v_ashrrev_i32_e32 v66, 1, v65
	s_movk_i32 s24, 0xffc0
	v_and_or_b32 v64, v65, 64, v64
	v_and_or_b32 v65, v66, s24, v67
	v_lshl_add_u32 v65, s0, 7, v65
	v_cvt_pk_bf16_f32 v60, v60, v61
	v_cvt_pk_bf16_f32 v61, v62, v63
	v_cvt_pk_bf16_f32 v62, v56, v57
	v_mov_b64_e32 v[56:57], s[70:71]
	v_cvt_pk_bf16_f32 v44, v44, v45
	v_cvt_pk_bf16_f32 v45, v46, v47
	v_cvt_pk_bf16_f32 v46, v40, v41
	v_or_b32_e32 v40, 16, v65
	v_cvt_pk_bf16_f32 v28, v28, v29
	v_cvt_pk_bf16_f32 v29, v30, v31
	v_cvt_pk_bf16_f32 v30, v24, v25
	v_or_b32_e32 v24, 32, v65
	v_cvt_pk_bf16_f32 v12, v12, v13
	v_cvt_pk_bf16_f32 v13, v14, v15
	v_cvt_pk_bf16_f32 v14, v8, v9
	v_or_b32_e32 v8, 48, v65
	v_cvt_pk_bf16_f32 v63, v58, v59
	v_mad_i64_i32 v[58:59], s[24:25], v65, s56, v[56:57]
	s_lshl_b32 s28, s1, 8
	v_mad_i64_i32 v[40:41], s[0:1], v40, s56, v[56:57]
	v_mad_i64_i32 v[24:25], s[0:1], v24, s56, v[56:57]
	v_mad_i64_i32 v[8:9], s[0:1], v8, s56, v[56:57]
	v_lshl_add_u64 v[58:59], v[58:59], 0, s[28:29]
	v_lshlrev_b32_e32 v128, 1, v64
	v_lshl_add_u64 v[40:41], v[40:41], 0, s[28:29]
	v_lshl_add_u64 v[24:25], v[24:25], 0, s[28:29]
	v_lshl_add_u64 v[8:9], v[8:9], 0, s[28:29]
	v_lshl_add_u64 v[58:59], v[58:59], 0, v[128:129]
	v_cvt_pk_bf16_f32 v52, v52, v53
	v_cvt_pk_bf16_f32 v53, v54, v55
	v_cvt_pk_bf16_f32 v54, v48, v49
	v_cvt_pk_bf16_f32 v55, v50, v51
	v_cvt_pk_bf16_f32 v47, v42, v43
	v_lshl_add_u64 v[40:41], v[40:41], 0, v[128:129]
	v_cvt_pk_bf16_f32 v36, v36, v37
	v_cvt_pk_bf16_f32 v37, v38, v39
	v_cvt_pk_bf16_f32 v38, v32, v33
	v_cvt_pk_bf16_f32 v39, v34, v35
	v_cvt_pk_bf16_f32 v31, v26, v27
	v_lshl_add_u64 v[24:25], v[24:25], 0, v[128:129]
	v_cvt_pk_bf16_f32 v20, v20, v21
	v_cvt_pk_bf16_f32 v21, v22, v23
	v_cvt_pk_bf16_f32 v22, v16, v17
	v_cvt_pk_bf16_f32 v23, v18, v19
	v_cvt_pk_bf16_f32 v15, v10, v11
	v_lshl_add_u64 v[8:9], v[8:9], 0, v[128:129]
	v_cvt_pk_bf16_f32 v4, v4, v5
	v_cvt_pk_bf16_f32 v5, v6, v7
	v_cvt_pk_bf16_f32 v6, v0, v1
	v_cvt_pk_bf16_f32 v7, v2, v3
	global_store_dwordx4 v[58:59], v[60:63], off
	global_store_dwordx4 v[58:59], v[52:55], off offset:64
	global_store_dwordx4 v[40:41], v[44:47], off
	global_store_dwordx4 v[40:41], v[36:39], off offset:64
	global_store_dwordx4 v[24:25], v[28:31], off
	global_store_dwordx4 v[24:25], v[20:23], off offset:64
	global_store_dwordx4 v[8:9], v[12:15], off
	global_store_dwordx4 v[8:9], v[4:7], off offset:64

.LBB0_173:
	s_andn2_b64 vcc, exec, s[0:1]
	s_cbranch_vccnz .LBB0_177
	s_add_i32 s1, s39, 0xff00
	s_bfe_u32 s0, s1, 0xf0001
	s_mul_i32 s0, s0, 0xc30d
	s_lshr_b32 s0, s0, 20
	v_mov_b32_e32 v2, v208
	s_mul_i32 s24, s0, 42
	s_sub_i32 s1, s1, s24
	v_ashrrev_i32_e32 v3, 6, v2
	v_lshrrev_b32_e32 v0, 3, v2
	v_bfe_u32 v1, v2, 3, 3
	v_lshlrev_b32_e32 v5, 5, v3
	s_lshl_b32 s24, s1, 16
	v_readlane_b32 s30, v253, 31
	v_bitop3_b32 v4, v0, v2, 7 bitop3:0x28
	v_or_b32_e32 v0, v5, v1
	v_readlane_b32 s31, v253, 32
	s_add_u32 s24, s30, s24
	v_ashrrev_i32_e32 v1, 31, v0
	s_addc_u32 s25, s31, 0
	v_lshlrev_b64 v[0:1], 9, v[0:1]
	v_lshl_add_u64 v[0:1], s[24:25], 0, v[0:1]
	v_lshlrev_b32_e32 v128, 4, v4
	v_lshl_add_u64 v[64:65], v[0:1], 0, v[128:129]
	v_lshrrev_b32_e32 v0, 2, v2
	v_and_b32_e32 v0, 8, v0
	v_bfe_u32 v1, v2, 3, 2
	s_lshl_b32 s26, s0, 16
	v_or3_b32 v0, v0, v1, v5
	s_add_u32 s30, s37, s26
	v_ashrrev_i32_e32 v1, 31, v0
	s_addc_u32 s31, s38, 0
	v_lshlrev_b64 v[0:1], 9, v[0:1]
	v_lshlrev_b32_e32 v78, 12, v3
	v_lshl_add_u64 v[0:1], s[30:31], 0, v[0:1]
	v_readfirstlane_b32 s24, v78
	v_lshl_add_u64 v[66:67], v[0:1], 0, v[128:129]
	s_mov_b32 m0, s24
	s_mov_b64 s[24:25], 0x1000
	v_or_b32_e32 v0, 0x400, v78
	s_waitcnt lgkmcnt(0)
	s_barrier
	v_lshl_add_u64 v[68:69], v[64:65], 0, s[24:25]
	v_readfirstlane_b32 s24, v0
	v_or_b32_e32 v0, 0x800, v78
	global_load_lds_dwordx4 v[64:65], off
	s_mov_b32 m0, s24
	v_readfirstlane_b32 s24, v0
	global_load_lds_dwordx4 v[68:69], off
	s_mov_b64 s[30:31], 0x2000
	s_mov_b32 m0, s24
	s_mov_b64 s[24:25], 0x3000
	v_or_b32_e32 v0, 0xc00, v78
	v_lshl_add_u64 v[70:71], v[64:65], 0, s[30:31]
	v_lshl_add_u64 v[72:73], v[64:65], 0, s[24:25]
	v_readfirstlane_b32 s24, v0
	v_add_u32_e32 v0, 0x4000, v78
	global_load_lds_dwordx4 v[70:71], off
	s_mov_b32 m0, s24
	v_readfirstlane_b32 s24, v0
	v_add_u32_e32 v0, 0x4400, v78
	global_load_lds_dwordx4 v[72:73], off
	s_mov_b32 m0, s24
	v_readfirstlane_b32 s24, v0
	v_add_u32_e32 v4, 0x4800, v78
	global_load_lds_dwordx4 v[66:67], off
	v_lshl_add_u64 v[74:75], v[66:67], 0, s[30:31]
	s_mov_b32 m0, s24
	v_readfirstlane_b32 s24, v4
	global_load_lds_dwordx4 v[74:75], off
	v_lshl_add_u64 v[0:1], v[66:67], 0, s[50:51]
	s_mov_b32 m0, s24
	s_mov_b64 s[24:25], 0x2800
	global_load_lds_dwordx4 v[0:1], off
	v_add_u32_e32 v0, 0x4c00, v78
	v_lshl_add_u64 v[76:77], v[66:67], 0, s[24:25]
	v_readfirstlane_b32 s24, v0
	s_mov_b32 m0, s24
	v_and_b32_e32 v0, 7, v2
	global_load_lds_dwordx4 v[76:77], off
	v_lshlrev_b32_e32 v1, 7, v2
	v_lshlrev_b32_e32 v0, 4, v0
	v_and_b32_e32 v1, 0x780, v1
	v_bitop3_b32 v0, v0, v2, 48 bitop3:0x78
	v_or_b32_e32 v79, v0, v1
	v_bitop3_b32 v80, v0, 64, v1 bitop3:0x36
	v_lshlrev_b32_e32 v0, 6, v2
	v_and_b32_e32 v81, 0xffffe000, v0
	v_lshlrev_b32_e32 v0, 13, v3
	v_and_b32_e32 v0, 0x2000, v0
	v_or_b32_e32 v82, 0x4000, v0
	v_mov_b32_e32 v0, 0
	s_mov_b32 s24, 64
	s_mov_b32 s26, 0
	v_mov_b32_e32 v1, v0
	v_mov_b32_e32 v2, v0
	v_mov_b32_e32 v3, v0
	v_mov_b32_e32 v4, v0
	v_mov_b32_e32 v5, v0
	v_mov_b32_e32 v6, v0
	v_mov_b32_e32 v7, v0
	v_mov_b32_e32 v8, v0
	v_mov_b32_e32 v9, v0
	v_mov_b32_e32 v10, v0
	v_mov_b32_e32 v11, v0
	v_mov_b32_e32 v12, v0
	v_mov_b32_e32 v13, v0
	v_mov_b32_e32 v14, v0
	v_mov_b32_e32 v15, v0
	v_mov_b32_e32 v16, v0
	v_mov_b32_e32 v17, v0
	v_mov_b32_e32 v18, v0
	v_mov_b32_e32 v19, v0
	v_mov_b32_e32 v24, v0
	v_mov_b32_e32 v25, v0
	v_mov_b32_e32 v26, v0
	v_mov_b32_e32 v27, v0
	v_mov_b32_e32 v28, v0
	v_mov_b32_e32 v29, v0
	v_mov_b32_e32 v30, v0
	v_mov_b32_e32 v31, v0
	v_mov_b32_e32 v32, v0
	v_mov_b32_e32 v33, v0
	v_mov_b32_e32 v34, v0
	v_mov_b32_e32 v35, v0
	v_mov_b32_e32 v36, v0
	v_mov_b32_e32 v37, v0
	v_mov_b32_e32 v38, v0
	v_mov_b32_e32 v39, v0
	v_mov_b32_e32 v40, v0
	v_mov_b32_e32 v41, v0
	v_mov_b32_e32 v42, v0
	v_mov_b32_e32 v43, v0
	v_mov_b32_e32 v44, v0
	v_mov_b32_e32 v45, v0
	v_mov_b32_e32 v46, v0
	v_mov_b32_e32 v47, v0
	v_mov_b32_e32 v48, v0
	v_mov_b32_e32 v49, v0
	v_mov_b32_e32 v50, v0
	v_mov_b32_e32 v51, v0
	v_mov_b32_e32 v52, v0
	v_mov_b32_e32 v53, v0
	v_mov_b32_e32 v54, v0
	v_mov_b32_e32 v55, v0
	v_mov_b32_e32 v56, v0
	v_mov_b32_e32 v57, v0
	v_mov_b32_e32 v58, v0
	v_mov_b32_e32 v59, v0
	v_mov_b32_e32 v60, v0
	v_mov_b32_e32 v61, v0
	v_mov_b32_e32 v62, v0
	v_mov_b32_e32 v63, v0
	v_mov_b32_e32 v20, v0
	v_mov_b32_e32 v21, v0
	v_mov_b32_e32 v22, v0
	v_mov_b32_e32 v23, v0
	s_movk_i32 s30, 0x80
	s_mov_b32 s31, 0
	v_add_u32_e32 v83, 0x8000, v78
	s_nop 1
	v_readfirstlane_b32 s28, v83
	v_add_u32_e32 v86, 0x400, v83
	v_lshl_add_u64 v[84:85], v[64:65], 0, s[30:31]
	s_mov_b32 m0, s28
	v_readfirstlane_b32 s28, v86
	v_add_u32_e32 v86, 0x800, v83
	global_load_lds_dwordx4 v[84:85], off
	v_lshl_add_u64 v[84:85], v[68:69], 0, s[30:31]
	s_mov_b32 m0, s28
	v_readfirstlane_b32 s28, v86
	v_add_u32_e32 v86, 0xc00, v83
	global_load_lds_dwordx4 v[84:85], off
	v_lshl_add_u64 v[84:85], v[70:71], 0, s[30:31]
	s_mov_b32 m0, s28
	v_readfirstlane_b32 s28, v86
	v_add_u32_e32 v86, 0x4000, v83
	global_load_lds_dwordx4 v[84:85], off
	v_lshl_add_u64 v[84:85], v[72:73], 0, s[30:31]
	s_mov_b32 m0, s28
	v_readfirstlane_b32 s28, v86
	v_add_u32_e32 v88, 0x4400, v83
	global_load_lds_dwordx4 v[84:85], off
	v_lshl_add_u64 v[84:85], v[66:67], 0, s[30:31]
	s_mov_b32 m0, s28
	v_readfirstlane_b32 s28, v88
	global_load_lds_dwordx4 v[84:85], off
	v_lshl_add_u64 v[86:87], v[74:75], 0, s[30:31]
	s_mov_b32 m0, s28
	v_lshl_add_u64 v[84:85], v[84:85], 0, s[50:51]
	global_load_lds_dwordx4 v[86:87], off
	v_add_u32_e32 v86, 0x4800, v83
	v_add_u32_e32 v83, 0x4c00, v83
	v_readfirstlane_b32 s28, v86
	s_mov_b32 m0, s28
	v_readfirstlane_b32 s28, v83
	global_load_lds_dwordx4 v[84:85], off
	v_lshl_add_u64 v[84:85], v[76:77], 0, s[30:31]
	s_mov_b32 m0, s28
	s_nop 0
	global_load_lds_dwordx4 v[84:85], off
.LBB0_175:
	s_cmp_lt_i32 s24, 256
	s_cbranch_scc1 .LgpD_w8
	s_waitcnt vmcnt(0)
	s_branch .LgpD_wd

.LgpD_wd:
	s_and_b32 s28, s26, 0x8000
	s_waitcnt lgkmcnt(0)
	s_barrier
	v_add_u32_e32 v83, s28, v81
	v_or_b32_e32 v84, s28, v82
	v_add_u32_e32 v128, v83, v79
	v_add_u32_e32 v83, v83, v80
	v_add_u32_e32 v131, v84, v79
	v_add_u32_e32 v133, v84, v80
	ds_read_b128 v[84:87], v128
	ds_read_b128 v[88:91], v128 offset:2048
	ds_read_b128 v[92:95], v128 offset:4096
	ds_read_b128 v[96:99], v128 offset:6144
	ds_read_b128 v[100:103], v131
	ds_read_b128 v[104:107], v131 offset:2048
	ds_read_b128 v[108:111], v131 offset:4096
	ds_read_b128 v[112:115], v131 offset:6144
	ds_read_b128 v[116:119], v83
	ds_read_b128 v[120:123], v83 offset:2048
	ds_read_b128 v[124:127], v83 offset:4096
	ds_read_b128 v[134:137], v83 offset:6144
	ds_read_b128 v[138:141], v133
	ds_read_b128 v[142:145], v133 offset:2048
	ds_read_b128 v[146:149], v133 offset:4096
	ds_read_b128 v[150:153], v133 offset:6144
	s_waitcnt lgkmcnt(8)
	v_mfma_f32_16x16x32_bf16 v[60:63], v[100:103], v[84:87], v[60:63]
	v_mfma_f32_16x16x32_bf16 v[56:59], v[104:107], v[84:87], v[56:59]
	v_mfma_f32_16x16x32_bf16 v[52:55], v[108:111], v[84:87], v[52:55]
	v_mfma_f32_16x16x32_bf16 v[48:51], v[112:115], v[84:87], v[48:51]
	v_mfma_f32_16x16x32_bf16 v[44:47], v[100:103], v[88:91], v[44:47]
	v_mfma_f32_16x16x32_bf16 v[40:43], v[104:107], v[88:91], v[40:43]
	v_mfma_f32_16x16x32_bf16 v[36:39], v[108:111], v[88:91], v[36:39]
	v_mfma_f32_16x16x32_bf16 v[32:35], v[112:115], v[88:91], v[32:35]
	v_mfma_f32_16x16x32_bf16 v[28:31], v[100:103], v[92:95], v[28:31]
	v_mfma_f32_16x16x32_bf16 v[24:27], v[104:107], v[92:95], v[24:27]
	v_mfma_f32_16x16x32_bf16 v[16:19], v[108:111], v[92:95], v[16:19]
	v_mfma_f32_16x16x32_bf16 v[8:11], v[100:103], v[96:99], v[8:11]
	v_mfma_f32_16x16x32_bf16 v[4:7], v[104:107], v[96:99], v[4:7]
	v_mfma_f32_16x16x32_bf16 v[0:3], v[108:111], v[96:99], v[0:3]
	v_mfma_f32_16x16x32_bf16 v[20:23], v[112:115], v[96:99], v[20:23]
	v_mfma_f32_16x16x32_bf16 v[12:15], v[112:115], v[92:95], v[12:15]
	s_waitcnt lgkmcnt(0)
	s_barrier
	s_add_i32 s30, s24, 64
	s_cmp_ge_i32 s30, 256
	s_cbranch_scc1 .LgpD_nd
	v_add_u32_e32 v83, s28, v78
	s_ashr_i32 s31, s30, 31
	s_lshl_b64 s[30:31], s[30:31], 1
	v_readfirstlane_b32 s28, v83
	v_add_u32_e32 v86, 0x400, v83
	v_lshl_add_u64 v[84:85], v[64:65], 0, s[30:31]
	s_mov_b32 m0, s28
	v_readfirstlane_b32 s28, v86
	v_add_u32_e32 v86, 0x800, v83
	global_load_lds_dwordx4 v[84:85], off
	v_lshl_add_u64 v[84:85], v[68:69], 0, s[30:31]
	s_mov_b32 m0, s28
	v_readfirstlane_b32 s28, v86
	v_add_u32_e32 v86, 0xc00, v83
	global_load_lds_dwordx4 v[84:85], off
	v_lshl_add_u64 v[84:85], v[70:71], 0, s[30:31]
	s_mov_b32 m0, s28
	v_readfirstlane_b32 s28, v86
	v_add_u32_e32 v86, 0x4000, v83
	global_load_lds_dwordx4 v[84:85], off
	v_lshl_add_u64 v[84:85], v[72:73], 0, s[30:31]
	s_mov_b32 m0, s28
	v_readfirstlane_b32 s28, v86
	v_add_u32_e32 v88, 0x4400, v83
	global_load_lds_dwordx4 v[84:85], off
	v_lshl_add_u64 v[84:85], v[66:67], 0, s[30:31]
	s_mov_b32 m0, s28
	v_readfirstlane_b32 s28, v88
	global_load_lds_dwordx4 v[84:85], off
	v_lshl_add_u64 v[86:87], v[74:75], 0, s[30:31]
	s_mov_b32 m0, s28
	v_lshl_add_u64 v[84:85], v[84:85], 0, s[50:51]
	global_load_lds_dwordx4 v[86:87], off
	v_add_u32_e32 v86, 0x4800, v83
	v_add_u32_e32 v83, 0x4c00, v83
	v_readfirstlane_b32 s28, v86
	s_mov_b32 m0, s28
	v_readfirstlane_b32 s28, v83
	global_load_lds_dwordx4 v[84:85], off
	v_lshl_add_u64 v[84:85], v[76:77], 0, s[30:31]
	s_mov_b32 m0, s28
	s_nop 0
	global_load_lds_dwordx4 v[84:85], off
.LgpD_nd:
	s_nop 0
	v_mfma_f32_16x16x32_bf16 v[60:63], v[138:141], v[116:119], v[60:63]
	v_mfma_f32_16x16x32_bf16 v[56:59], v[142:145], v[116:119], v[56:59]
	v_mfma_f32_16x16x32_bf16 v[52:55], v[146:149], v[116:119], v[52:55]
	v_mfma_f32_16x16x32_bf16 v[48:51], v[150:153], v[116:119], v[48:51]
	v_mfma_f32_16x16x32_bf16 v[44:47], v[138:141], v[120:123], v[44:47]
	v_mfma_f32_16x16x32_bf16 v[40:43], v[142:145], v[120:123], v[40:43]
	v_mfma_f32_16x16x32_bf16 v[36:39], v[146:149], v[120:123], v[36:39]
	v_mfma_f32_16x16x32_bf16 v[32:35], v[150:153], v[120:123], v[32:35]
	v_mfma_f32_16x16x32_bf16 v[28:31], v[138:141], v[124:127], v[28:31]
	v_mfma_f32_16x16x32_bf16 v[24:27], v[142:145], v[124:127], v[24:27]
	v_mfma_f32_16x16x32_bf16 v[16:19], v[146:149], v[124:127], v[16:19]
	v_mfma_f32_16x16x32_bf16 v[12:15], v[150:153], v[124:127], v[12:15]
	v_mfma_f32_16x16x32_bf16 v[8:11], v[138:141], v[134:137], v[8:11]
	v_mfma_f32_16x16x32_bf16 v[4:7], v[142:145], v[134:137], v[4:7]
	v_mfma_f32_16x16x32_bf16 v[0:3], v[146:149], v[134:137], v[0:3]
	v_mfma_f32_16x16x32_bf16 v[20:23], v[150:153], v[134:137], v[20:23]
	s_add_i32 s24, s24, 64
	s_add_i32 s26, s26, 0x8000
	s_cmp_lg_u32 s26, 0x20000
	s_cbranch_scc1 .LBB0_175
	s_waitcnt vmcnt(0)
	v_mov_b32_e32 v64, v208
	s_waitcnt lgkmcnt(0)
	s_barrier
	v_mov_b32_e32 v65, v208
	v_and_b32_e32 v67, 15, v64
	v_lshrrev_b32_e32 v64, 1, v64
	v_and_b32_e32 v64, 24, v64
	v_ashrrev_i32_e32 v66, 1, v65
	s_movk_i32 s24, 0xffc0
	s_lshl_b32 s1, s1, 7
	v_and_or_b32 v64, v65, 64, v64
	v_and_or_b32 v65, v66, s24, v67
	s_and_b32 s1, s1, 0xff80
	v_cvt_pk_bf16_f32 v60, v60, v61
	v_cvt_pk_bf16_f32 v61, v62, v63
	v_cvt_pk_bf16_f32 v62, v56, v57
	v_add_u32_e32 v56, s1, v65
	v_cvt_pk_bf16_f32 v44, v44, v45
	v_cvt_pk_bf16_f32 v45, v46, v47
	v_cvt_pk_bf16_f32 v46, v40, v41
	v_or_b32_e32 v40, 16, v56
	v_cvt_pk_bf16_f32 v28, v28, v29
	v_cvt_pk_bf16_f32 v29, v30, v31
	v_cvt_pk_bf16_f32 v30, v24, v25
	v_or_b32_e32 v24, 32, v56
	v_cvt_pk_bf16_f32 v8, v8, v9
	v_cvt_pk_bf16_f32 v9, v10, v11
	v_cvt_pk_bf16_f32 v10, v4, v5
	v_or_b32_e32 v4, 48, v56
	v_ashrrev_i32_e32 v57, 31, v56
	v_readlane_b32 s24, v253, 17
	v_ashrrev_i32_e32 v41, 31, v40
	v_ashrrev_i32_e32 v25, 31, v24
	v_ashrrev_i32_e32 v5, 31, v4
	v_cvt_pk_bf16_f32 v63, v58, v59
	v_lshlrev_b64 v[58:59], 11, v[56:57]
	v_readlane_b32 s25, v253, 18
	v_lshlrev_b64 v[40:41], 11, v[40:41]
	v_lshlrev_b64 v[24:25], 11, v[24:25]
	v_lshlrev_b64 v[4:5], 11, v[4:5]
	v_lshl_add_u64 v[58:59], s[24:25], 0, v[58:59]
	s_lshl_b32 s28, s0, 8
	v_lshl_add_u64 v[40:41], s[24:25], 0, v[40:41]
	v_lshl_add_u64 v[24:25], s[24:25], 0, v[24:25]
	v_lshl_add_u64 v[4:5], s[24:25], 0, v[4:5]
	v_lshl_add_u64 v[58:59], v[58:59], 0, s[28:29]
	v_lshlrev_b32_e32 v128, 1, v64
	v_lshl_add_u64 v[40:41], v[40:41], 0, s[28:29]
	v_lshl_add_u64 v[24:25], v[24:25], 0, s[28:29]
	v_lshl_add_u64 v[4:5], v[4:5], 0, s[28:29]
	v_lshl_add_u64 v[58:59], v[58:59], 0, v[128:129]
	v_cvt_pk_bf16_f32 v52, v52, v53
	v_cvt_pk_bf16_f32 v53, v54, v55
	v_cvt_pk_bf16_f32 v54, v48, v49
	v_cvt_pk_bf16_f32 v55, v50, v51
	v_cvt_pk_bf16_f32 v47, v42, v43
	v_lshl_add_u64 v[40:41], v[40:41], 0, v[128:129]
	v_cvt_pk_bf16_f32 v36, v36, v37
	v_cvt_pk_bf16_f32 v37, v38, v39
	v_cvt_pk_bf16_f32 v38, v32, v33
	v_cvt_pk_bf16_f32 v39, v34, v35
	v_cvt_pk_bf16_f32 v31, v26, v27
	v_lshl_add_u64 v[24:25], v[24:25], 0, v[128:129]
	v_cvt_pk_bf16_f32 v16, v16, v17
	v_cvt_pk_bf16_f32 v17, v18, v19
	v_cvt_pk_bf16_f32 v18, v12, v13
	v_cvt_pk_bf16_f32 v19, v14, v15
	v_cvt_pk_bf16_f32 v11, v6, v7
	v_lshl_add_u64 v[4:5], v[4:5], 0, v[128:129]
	v_cvt_pk_bf16_f32 v0, v0, v1
	v_cvt_pk_bf16_f32 v1, v2, v3
	v_cvt_pk_bf16_f32 v2, v20, v21
	v_cvt_pk_bf16_f32 v3, v22, v23
	v_readlane_b32 s28, v255, 25
	global_store_dwordx4 v[58:59], v[60:63], off
	global_store_dwordx4 v[58:59], v[52:55], off offset:64
	global_store_dwordx4 v[40:41], v[44:47], off
	global_store_dwordx4 v[40:41], v[36:39], off offset:64
	global_store_dwordx4 v[24:25], v[28:31], off
	global_store_dwordx4 v[24:25], v[16:19], off offset:64
	global_store_dwordx4 v[4:5], v[8:11], off
	global_store_dwordx4 v[4:5], v[0:3], off offset:64

.LBB0_190:
	s_cmpk_gt_i32 s55, 0x13f
	s_mov_b64 s[38:39], -1
	s_cbranch_scc0 .LBB0_224
	s_cmpk_gt_u32 s55, 0x27f
	s_cbranch_scc0 .LBB0_202
	s_cmpk_gt_u32 s55, 0x28f
	s_cbranch_scc0 .LBB0_196
	s_add_i32 s25, s55, 0x70
	s_and_b32 s24, s25, 0xff
	s_mulk_i32 s24, 0xcd
	s_bfe_u32 s24, s24, 0x3000d
	s_mul_i32 s26, s24, 40
	s_sub_i32 s25, s25, s26
	s_and_b32 s25, s25, 0xff
	s_mul_i32 s26, s25, 0x1b0000
	v_mov_b32_e32 v4, v208
	s_add_u32 s38, s82, s26
	s_addc_u32 s39, s83, 0
	v_ashrrev_i32_e32 v5, 6, v4
	v_lshrrev_b32_e32 v0, 3, v4
	s_mul_i32 s26, s24, 0x18000
	v_bfe_u32 v1, v4, 3, 3
	v_bitop3_b32 v2, v0, v4, 7 bitop3:0x28
	v_lshlrev_b32_e32 v3, 5, v5
	s_add_u32 s40, s50, s26
	v_or_b32_e32 v6, v3, v1
	v_mov_b64_e32 v[0:1], s[38:39]
	v_lshlrev_b32_e32 v128, 4, v2
	v_lshrrev_b32_e32 v2, 2, v4
	s_addc_u32 s41, s51, 0
	v_mad_i64_i32 v[0:1], s[38:39], v6, s58, v[0:1]
	v_and_b32_e32 v2, 8, v2
	v_bfe_u32 v6, v4, 3, 2
	v_lshl_add_u64 v[0:1], v[0:1], 0, v[128:129]
	s_mov_b64 s[38:39], 0x5160c40
	v_or3_b32 v6, v2, v6, v3
	v_mov_b64_e32 v[2:3], s[40:41]
	s_movk_i32 s26, 0x300
	v_lshl_add_u64 v[74:75], v[0:1], 0, s[38:39]
	v_mad_i64_i32 v[2:3], s[38:39], v6, s26, v[2:3]
	v_lshlrev_b32_e32 v73, 12, v5
	s_mov_b64 s[38:39], 0x517bc40
	v_lshl_add_u64 v[76:77], v[2:3], 0, v[128:129]
	v_readfirstlane_b32 s26, v73
	v_lshl_add_u64 v[78:79], v[0:1], 0, s[38:39]
	v_or_b32_e32 v2, 0x400, v73
	s_mov_b64 s[38:39], 0x5196c40
	s_waitcnt lgkmcnt(0)
	s_barrier
	s_mov_b32 m0, s26
	v_readfirstlane_b32 s26, v2
	v_lshl_add_u64 v[80:81], v[0:1], 0, s[38:39]
	v_or_b32_e32 v2, 0x800, v73
	s_mov_b64 s[38:39], 0x51b1c40
	global_load_lds_dwordx4 v[74:75], off
	s_mov_b32 m0, s26
	v_readfirstlane_b32 s26, v2
	v_lshl_add_u64 v[82:83], v[0:1], 0, s[38:39]
	v_or_b32_e32 v0, 0xc00, v73
	global_load_lds_dwordx4 v[78:79], off
	s_mov_b32 m0, s26
	v_readfirstlane_b32 s26, v0
	v_add_u32_e32 v0, 0x4000, v73
	global_load_lds_dwordx4 v[80:81], off
	s_mov_b32 m0, s26
	v_readfirstlane_b32 s26, v0
	v_add_u32_e32 v0, 0x4400, v73
	global_load_lds_dwordx4 v[82:83], off
	s_mov_b32 m0, s26
	s_mov_b64 s[38:39], 0x3000
	v_readfirstlane_b32 s26, v0
	v_add_u32_e32 v2, 0x4800, v73
	global_load_lds_dwordx4 v[76:77], off
	v_lshl_add_u64 v[84:85], v[76:77], 0, s[38:39]
	s_mov_b32 m0, s26
	s_mov_b64 s[42:43], 0xc00
	v_readfirstlane_b32 s26, v2
	global_load_lds_dwordx4 v[84:85], off
	v_lshl_add_u64 v[0:1], v[76:77], 0, s[42:43]
	s_mov_b32 m0, s26
	s_mov_b64 s[38:39], 0x3c00
	global_load_lds_dwordx4 v[0:1], off
	v_add_u32_e32 v0, 0x4c00, v73
	v_lshl_add_u64 v[86:87], v[76:77], 0, s[38:39]
	v_readfirstlane_b32 s26, v0
	s_mov_b32 m0, s26
	v_and_b32_e32 v0, 7, v4
	global_load_lds_dwordx4 v[86:87], off
	v_lshlrev_b32_e32 v1, 7, v4
	v_lshlrev_b32_e32 v0, 4, v0
	v_and_b32_e32 v1, 0x780, v1
	v_bitop3_b32 v0, v0, v4, 48 bitop3:0x78
	v_or_b32_e32 v88, v0, v1
	v_bitop3_b32 v89, v0, 64, v1 bitop3:0x36
	v_lshlrev_b32_e32 v0, 6, v4
	v_and_b32_e32 v90, 0xffffe000, v0
	v_lshlrev_b32_e32 v0, 13, v5
	v_and_b32_e32 v0, 0x2000, v0
	v_or_b32_e32 v91, 0x4000, v0
	v_mov_b32_e32 v0, 0
	s_mov_b32 s26, 64
	s_mov_b32 s38, 0
	v_mov_b32_e32 v1, v0
	v_mov_b32_e32 v2, v0
	v_mov_b32_e32 v3, v0
	v_mov_b32_e32 v4, v0
	v_mov_b32_e32 v5, v0
	v_mov_b32_e32 v6, v0
	v_mov_b32_e32 v7, v0
	v_mov_b32_e32 v8, v0
	v_mov_b32_e32 v9, v0
	v_mov_b32_e32 v10, v0
	v_mov_b32_e32 v11, v0
	v_mov_b32_e32 v12, v0
	v_mov_b32_e32 v13, v0
	v_mov_b32_e32 v14, v0
	v_mov_b32_e32 v15, v0
	v_mov_b32_e32 v16, v0
	v_mov_b32_e32 v17, v0
	v_mov_b32_e32 v18, v0
	v_mov_b32_e32 v19, v0
	v_mov_b32_e32 v20, v0
	v_mov_b32_e32 v21, v0
	v_mov_b32_e32 v22, v0
	v_mov_b32_e32 v23, v0
	v_mov_b32_e32 v28, v0
	v_mov_b32_e32 v29, v0
	v_mov_b32_e32 v30, v0
	v_mov_b32_e32 v31, v0
	v_mov_b32_e32 v32, v0
	v_mov_b32_e32 v33, v0
	v_mov_b32_e32 v34, v0
	v_mov_b32_e32 v35, v0
	v_mov_b32_e32 v36, v0
	v_mov_b32_e32 v37, v0
	v_mov_b32_e32 v38, v0
	v_mov_b32_e32 v39, v0
	v_mov_b32_e32 v40, v0
	v_mov_b32_e32 v41, v0
	v_mov_b32_e32 v42, v0
	v_mov_b32_e32 v43, v0
	v_mov_b32_e32 v44, v0
	v_mov_b32_e32 v45, v0
	v_mov_b32_e32 v46, v0
	v_mov_b32_e32 v47, v0
	v_mov_b32_e32 v48, v0
	v_mov_b32_e32 v49, v0
	v_mov_b32_e32 v50, v0
	v_mov_b32_e32 v51, v0
	v_mov_b32_e32 v52, v0
	v_mov_b32_e32 v53, v0
	v_mov_b32_e32 v54, v0
	v_mov_b32_e32 v55, v0
	v_mov_b32_e32 v56, v0
	v_mov_b32_e32 v57, v0
	v_mov_b32_e32 v58, v0
	v_mov_b32_e32 v59, v0
	v_mov_b32_e32 v60, v0
	v_mov_b32_e32 v61, v0
	v_mov_b32_e32 v62, v0
	v_mov_b32_e32 v63, v0
	v_mov_b32_e32 v24, v0
	v_mov_b32_e32 v25, v0
	v_mov_b32_e32 v26, v0
	v_mov_b32_e32 v27, v0
	s_movk_i32 s40, 0x80
	s_mov_b32 s41, 0
	v_add_u32_e32 v96, 0x8000, v73
	s_nop 1
	v_readfirstlane_b32 s39, v96
	v_add_u32_e32 v94, 0x400, v96
	v_lshl_add_u64 v[92:93], v[74:75], 0, s[40:41]
	s_mov_b32 m0, s39
	v_readfirstlane_b32 s39, v94
	v_add_u32_e32 v94, 0x800, v96
	global_load_lds_dwordx4 v[92:93], off
	v_lshl_add_u64 v[92:93], v[78:79], 0, s[40:41]
	s_mov_b32 m0, s39
	v_readfirstlane_b32 s39, v94
	v_add_u32_e32 v94, 0xc00, v96
	global_load_lds_dwordx4 v[92:93], off
	v_lshl_add_u64 v[92:93], v[80:81], 0, s[40:41]
	s_mov_b32 m0, s39
	v_readfirstlane_b32 s39, v94
	v_add_u32_e32 v94, 0x4000, v96
	global_load_lds_dwordx4 v[92:93], off
	v_lshl_add_u64 v[92:93], v[82:83], 0, s[40:41]
	s_mov_b32 m0, s39
	v_readfirstlane_b32 s39, v94
	v_add_u32_e32 v97, 0x4400, v96
	global_load_lds_dwordx4 v[92:93], off
	v_lshl_add_u64 v[92:93], v[76:77], 0, s[40:41]
	s_mov_b32 m0, s39
	v_readfirstlane_b32 s39, v97
	global_load_lds_dwordx4 v[92:93], off
	v_lshl_add_u64 v[94:95], v[84:85], 0, s[40:41]
	s_mov_b32 m0, s39
	v_lshl_add_u64 v[92:93], v[92:93], 0, s[42:43]
	global_load_lds_dwordx4 v[94:95], off
	v_add_u32_e32 v94, 0x4800, v96
	s_nop 0
	v_readfirstlane_b32 s39, v94
	v_add_u32_e32 v94, 0x4c00, v96
	s_mov_b32 m0, s39
	v_readfirstlane_b32 s39, v94
	global_load_lds_dwordx4 v[92:93], off
	v_lshl_add_u64 v[92:93], v[86:87], 0, s[40:41]
	s_mov_b32 m0, s39
	s_nop 0
	global_load_lds_dwordx4 v[92:93], off
.LBB0_194:
	s_cmp_lt_i32 s26, 384
	s_cbranch_scc1 .LgpC_w8
	s_waitcnt vmcnt(0)
	s_branch .LgpC_wd

.LgpC_wd:
	s_and_b32 s39, s38, 0x8000
	s_waitcnt lgkmcnt(0)
	s_barrier
	v_add_u32_e32 v92, s39, v90
	v_add_u32_e32 v128, v92, v88
	v_add_u32_e32 v131, v92, v89
	v_or_b32_e32 v92, s39, v91
	v_add_u32_e32 v133, v92, v88
	v_add_u32_e32 v162, v92, v89
	ds_read_b128 v[92:95], v128
	ds_read_b128 v[96:99], v128 offset:2048
	ds_read_b128 v[100:103], v128 offset:4096
	ds_read_b128 v[104:107], v128 offset:6144
	ds_read_b128 v[108:111], v133
	ds_read_b128 v[112:115], v133 offset:2048
	ds_read_b128 v[116:119], v133 offset:4096
	ds_read_b128 v[120:123], v133 offset:6144
	ds_read_b128 v[124:127], v131
	ds_read_b128 v[134:137], v131 offset:2048
	ds_read_b128 v[138:141], v131 offset:4096
	ds_read_b128 v[142:145], v131 offset:6144
	ds_read_b128 v[146:149], v162
	ds_read_b128 v[150:153], v162 offset:2048
	ds_read_b128 v[154:157], v162 offset:4096
	ds_read_b128 v[158:161], v162 offset:6144
	s_waitcnt lgkmcnt(8)
	v_mfma_f32_16x16x32_bf16 v[60:63], v[108:111], v[92:95], v[60:63]
	v_mfma_f32_16x16x32_bf16 v[56:59], v[112:115], v[92:95], v[56:59]
	v_mfma_f32_16x16x32_bf16 v[52:55], v[116:119], v[92:95], v[52:55]
	v_mfma_f32_16x16x32_bf16 v[48:51], v[120:123], v[92:95], v[48:51]
	v_mfma_f32_16x16x32_bf16 v[44:47], v[108:111], v[96:99], v[44:47]
	v_mfma_f32_16x16x32_bf16 v[40:43], v[112:115], v[96:99], v[40:43]
	v_mfma_f32_16x16x32_bf16 v[36:39], v[116:119], v[96:99], v[36:39]
	v_mfma_f32_16x16x32_bf16 v[32:35], v[120:123], v[96:99], v[32:35]
	v_mfma_f32_16x16x32_bf16 v[28:31], v[108:111], v[100:103], v[28:31]
	v_mfma_f32_16x16x32_bf16 v[20:23], v[112:115], v[100:103], v[20:23]
	v_mfma_f32_16x16x32_bf16 v[16:19], v[116:119], v[100:103], v[16:19]
	v_mfma_f32_16x16x32_bf16 v[8:11], v[108:111], v[104:107], v[8:11]
	v_mfma_f32_16x16x32_bf16 v[4:7], v[112:115], v[104:107], v[4:7]
	v_mfma_f32_16x16x32_bf16 v[0:3], v[116:119], v[104:107], v[0:3]
	v_mfma_f32_16x16x32_bf16 v[24:27], v[120:123], v[104:107], v[24:27]
	v_mfma_f32_16x16x32_bf16 v[12:15], v[120:123], v[100:103], v[12:15]
	s_waitcnt lgkmcnt(0)
	s_barrier
	s_add_i32 s40, s26, 64
	s_cmp_ge_i32 s40, 384
	s_cbranch_scc1 .LgpC_nd
	v_add_u32_e32 v96, s39, v73
	s_ashr_i32 s41, s40, 31
	s_lshl_b64 s[40:41], s[40:41], 1
	v_readfirstlane_b32 s39, v96
	v_add_u32_e32 v94, 0x400, v96
	v_lshl_add_u64 v[92:93], v[74:75], 0, s[40:41]
	s_mov_b32 m0, s39
	v_readfirstlane_b32 s39, v94
	v_add_u32_e32 v94, 0x800, v96
	global_load_lds_dwordx4 v[92:93], off
	v_lshl_add_u64 v[92:93], v[78:79], 0, s[40:41]
	s_mov_b32 m0, s39
	v_readfirstlane_b32 s39, v94
	v_add_u32_e32 v94, 0xc00, v96
	global_load_lds_dwordx4 v[92:93], off
	v_lshl_add_u64 v[92:93], v[80:81], 0, s[40:41]
	s_mov_b32 m0, s39
	v_readfirstlane_b32 s39, v94
	v_add_u32_e32 v94, 0x4000, v96
	global_load_lds_dwordx4 v[92:93], off
	v_lshl_add_u64 v[92:93], v[82:83], 0, s[40:41]
	s_mov_b32 m0, s39
	v_readfirstlane_b32 s39, v94
	v_add_u32_e32 v97, 0x4400, v96
	global_load_lds_dwordx4 v[92:93], off
	v_lshl_add_u64 v[92:93], v[76:77], 0, s[40:41]
	s_mov_b32 m0, s39
	v_readfirstlane_b32 s39, v97
	global_load_lds_dwordx4 v[92:93], off
	v_lshl_add_u64 v[94:95], v[84:85], 0, s[40:41]
	s_mov_b32 m0, s39
	v_lshl_add_u64 v[92:93], v[92:93], 0, s[42:43]
	global_load_lds_dwordx4 v[94:95], off
	v_add_u32_e32 v94, 0x4800, v96
	s_nop 0
	v_readfirstlane_b32 s39, v94
	v_add_u32_e32 v94, 0x4c00, v96
	s_mov_b32 m0, s39
	v_readfirstlane_b32 s39, v94
	global_load_lds_dwordx4 v[92:93], off
	v_lshl_add_u64 v[92:93], v[86:87], 0, s[40:41]
	s_mov_b32 m0, s39
	s_nop 0
	global_load_lds_dwordx4 v[92:93], off
.LgpC_nd:
	s_nop 0
	v_mfma_f32_16x16x32_bf16 v[60:63], v[146:149], v[124:127], v[60:63]
	v_mfma_f32_16x16x32_bf16 v[56:59], v[150:153], v[124:127], v[56:59]
	v_mfma_f32_16x16x32_bf16 v[52:55], v[154:157], v[124:127], v[52:55]
	v_mfma_f32_16x16x32_bf16 v[48:51], v[158:161], v[124:127], v[48:51]
	v_mfma_f32_16x16x32_bf16 v[44:47], v[146:149], v[134:137], v[44:47]
	v_mfma_f32_16x16x32_bf16 v[40:43], v[150:153], v[134:137], v[40:43]
	v_mfma_f32_16x16x32_bf16 v[36:39], v[154:157], v[134:137], v[36:39]
	v_mfma_f32_16x16x32_bf16 v[32:35], v[158:161], v[134:137], v[32:35]
	v_mfma_f32_16x16x32_bf16 v[28:31], v[146:149], v[138:141], v[28:31]
	v_mfma_f32_16x16x32_bf16 v[20:23], v[150:153], v[138:141], v[20:23]
	v_mfma_f32_16x16x32_bf16 v[16:19], v[154:157], v[138:141], v[16:19]
	v_mfma_f32_16x16x32_bf16 v[12:15], v[158:161], v[138:141], v[12:15]
	v_mfma_f32_16x16x32_bf16 v[8:11], v[146:149], v[142:145], v[8:11]
	v_mfma_f32_16x16x32_bf16 v[4:7], v[150:153], v[142:145], v[4:7]
	v_mfma_f32_16x16x32_bf16 v[0:3], v[154:157], v[142:145], v[0:3]
	v_mfma_f32_16x16x32_bf16 v[24:27], v[158:161], v[142:145], v[24:27]
	s_add_i32 s26, s26, 64
	s_add_i32 s38, s38, 0x8000
	s_cmp_lg_u32 s38, 0x30000
	s_cbranch_scc1 .LBB0_194
	s_waitcnt vmcnt(0)
	v_mov_b32_e32 v73, v208
	s_waitcnt lgkmcnt(0)
	s_barrier
	v_mov_b32_e32 v74, v208
	v_and_b32_e32 v76, 15, v73
	v_lshrrev_b32_e32 v73, 1, v73
	v_and_b32_e32 v73, 24, v73
	v_ashrrev_i32_e32 v75, 1, v74
	s_movk_i32 s26, 0xffc0
	v_and_or_b32 v73, v74, 64, v73
	v_and_or_b32 v74, v75, s26, v76
	v_readlane_b32 s38, v253, 3
	v_lshl_add_u32 v74, s25, 7, v74
	v_readlane_b32 s39, v253, 4
	v_cvt_pk_bf16_f32 v60, v60, v61
	v_cvt_pk_bf16_f32 v61, v62, v63
	v_cvt_pk_bf16_f32 v62, v56, v57
	v_mov_b64_e32 v[56:57], s[38:39]
	s_movk_i32 s26, 0x600
	v_cvt_pk_bf16_f32 v44, v44, v45
	v_cvt_pk_bf16_f32 v45, v46, v47
	v_cvt_pk_bf16_f32 v46, v40, v41
	v_or_b32_e32 v40, 16, v74
	v_cvt_pk_bf16_f32 v28, v28, v29
	v_cvt_pk_bf16_f32 v29, v30, v31
	v_cvt_pk_bf16_f32 v30, v20, v21
	v_or_b32_e32 v20, 32, v74
	v_cvt_pk_bf16_f32 v8, v8, v9
	v_cvt_pk_bf16_f32 v9, v10, v11
	v_cvt_pk_bf16_f32 v10, v4, v5
	v_or_b32_e32 v4, 48, v74
	v_cvt_pk_bf16_f32 v63, v58, v59
	v_mad_i64_i32 v[58:59], s[38:39], v74, s26, v[56:57]
	s_lshl_b32 s28, s24, 8
	v_mad_i64_i32 v[40:41], s[24:25], v40, s26, v[56:57]
	v_mad_i64_i32 v[20:21], s[24:25], v20, s26, v[56:57]
	v_mad_i64_i32 v[4:5], s[24:25], v4, s26, v[56:57]
	v_lshl_add_u64 v[58:59], v[58:59], 0, s[28:29]
	v_lshlrev_b32_e32 v128, 1, v73
	v_lshl_add_u64 v[40:41], v[40:41], 0, s[28:29]
	v_lshl_add_u64 v[20:21], v[20:21], 0, s[28:29]
	v_lshl_add_u64 v[4:5], v[4:5], 0, s[28:29]
	v_lshl_add_u64 v[58:59], v[58:59], 0, v[128:129]
	v_cvt_pk_bf16_f32 v52, v52, v53
	v_cvt_pk_bf16_f32 v53, v54, v55
	v_cvt_pk_bf16_f32 v54, v48, v49
	v_cvt_pk_bf16_f32 v55, v50, v51
	v_cvt_pk_bf16_f32 v47, v42, v43
	v_lshl_add_u64 v[40:41], v[40:41], 0, v[128:129]
	v_cvt_pk_bf16_f32 v36, v36, v37
	v_cvt_pk_bf16_f32 v37, v38, v39
	v_cvt_pk_bf16_f32 v38, v32, v33
	v_cvt_pk_bf16_f32 v39, v34, v35
	v_cvt_pk_bf16_f32 v31, v22, v23
	v_lshl_add_u64 v[20:21], v[20:21], 0, v[128:129]
	v_cvt_pk_bf16_f32 v16, v16, v17
	v_cvt_pk_bf16_f32 v17, v18, v19
	v_cvt_pk_bf16_f32 v18, v12, v13
	v_cvt_pk_bf16_f32 v19, v14, v15
	v_cvt_pk_bf16_f32 v11, v6, v7
	v_lshl_add_u64 v[4:5], v[4:5], 0, v[128:129]
	v_cvt_pk_bf16_f32 v0, v0, v1
	v_cvt_pk_bf16_f32 v1, v2, v3
	v_cvt_pk_bf16_f32 v2, v24, v25
	v_cvt_pk_bf16_f32 v3, v26, v27
	global_store_dwordx4 v[58:59], v[60:63], off
	global_store_dwordx4 v[58:59], v[52:55], off offset:64
	global_store_dwordx4 v[40:41], v[44:47], off
	global_store_dwordx4 v[40:41], v[36:39], off offset:64
	global_store_dwordx4 v[20:21], v[28:31], off
	global_store_dwordx4 v[20:21], v[16:19], off offset:64
	global_store_dwordx4 v[4:5], v[8:11], off
	global_store_dwordx4 v[4:5], v[0:3], off offset:64
	s_mov_b64 s[38:39], 0
	s_movk_i32 s26, 0xff

.LBB0_251:
	s_mul_hi_i32 s0, s27, 0x66666667
	s_lshr_b32 s1, s0, 31
	s_ashr_i32 s0, s0, 4
	s_add_i32 s0, s0, s1
	s_mul_i32 s1, s0, 40
	v_mov_b32_e32 v2, v208
	s_sub_i32 s30, s27, s1
	s_ashr_i32 s31, s30, 31
	v_ashrrev_i32_e32 v3, 6, v2
	v_lshrrev_b32_e32 v0, 3, v2
	v_bfe_u32 v1, v2, 3, 3
	v_lshlrev_b32_e32 v5, 5, v3
	s_lshl_b64 s[36:37], s[30:31], 18
	v_readlane_b32 s38, v251, 27
	v_bitop3_b32 v4, v0, v2, 7 bitop3:0x28
	v_or_b32_e32 v0, v5, v1
	v_readlane_b32 s39, v251, 28
	s_add_u32 s36, s38, s36
	v_ashrrev_i32_e32 v1, 31, v0
	s_addc_u32 s37, s39, s37
	v_lshlrev_b64 v[0:1], 11, v[0:1]
	v_lshl_add_u64 v[0:1], s[36:37], 0, v[0:1]
	v_lshlrev_b32_e32 v128, 4, v4
	v_lshl_add_u64 v[64:65], v[0:1], 0, v[128:129]
	v_lshrrev_b32_e32 v0, 2, v2
	s_ashr_i32 s1, s0, 31
	v_and_b32_e32 v0, 8, v0
	v_bfe_u32 v1, v2, 3, 2
	s_lshl_b64 s[38:39], s[0:1], 18
	v_or3_b32 v0, v0, v1, v5
	s_add_u32 s38, s24, s38
	v_ashrrev_i32_e32 v1, 31, v0
	s_addc_u32 s39, s25, s39
	v_lshlrev_b64 v[0:1], 11, v[0:1]
	v_lshl_add_u64 v[0:1], s[38:39], 0, v[0:1]
	v_lshlrev_b32_e32 v80, 12, v3
	v_lshl_add_u64 v[66:67], v[0:1], 0, v[128:129]
	v_readfirstlane_b32 s1, v80
	v_or_b32_e32 v0, 0x400, v80
	s_waitcnt lgkmcnt(0)
	s_barrier
	s_mov_b32 m0, s1
	s_mov_b64 s[36:37], 0x4000
	v_readfirstlane_b32 s1, v0
	v_or_b32_e32 v0, 0x800, v80
	global_load_lds_dwordx4 v[64:65], off
	v_lshl_add_u64 v[68:69], v[64:65], 0, s[36:37]
	s_mov_b32 m0, s1
	s_mov_b64 s[36:37], 0x8000
	v_readfirstlane_b32 s1, v0
	v_or_b32_e32 v0, 0xc00, v80
	global_load_lds_dwordx4 v[68:69], off
	v_lshl_add_u64 v[70:71], v[64:65], 0, s[36:37]
	s_mov_b32 m0, s1
	s_mov_b64 s[38:39], 0xc000
	v_readfirstlane_b32 s1, v0
	v_add_u32_e32 v0, 0x4000, v80
	global_load_lds_dwordx4 v[70:71], off
	v_lshl_add_u64 v[72:73], v[64:65], 0, s[38:39]
	s_mov_b32 m0, s1
	v_readfirstlane_b32 s1, v0
	v_add_u32_e32 v0, 0x4400, v80
	global_load_lds_dwordx4 v[72:73], off
	s_mov_b32 m0, s1
	v_readfirstlane_b32 s1, v0
	v_add_u32_e32 v0, 0x4800, v80
	global_load_lds_dwordx4 v[66:67], off
	v_lshl_add_u64 v[74:75], v[66:67], 0, s[36:37]
	s_mov_b32 m0, s1
	s_mov_b64 s[36:37], 0x2000
	v_readfirstlane_b32 s1, v0
	v_add_u32_e32 v0, 0x4c00, v80
	global_load_lds_dwordx4 v[74:75], off
	v_lshl_add_u64 v[76:77], v[66:67], 0, s[36:37]
	s_mov_b32 m0, s1
	s_mov_b64 s[36:37], 0xa000
	v_readfirstlane_b32 s1, v0
	global_load_lds_dwordx4 v[76:77], off
	v_lshl_add_u64 v[78:79], v[66:67], 0, s[36:37]
	s_mov_b32 m0, s1
	v_and_b32_e32 v0, 7, v2
	global_load_lds_dwordx4 v[78:79], off
	v_lshlrev_b32_e32 v1, 7, v2
	v_lshlrev_b32_e32 v0, 4, v0
	v_and_b32_e32 v1, 0x780, v1
	v_bitop3_b32 v0, v0, v2, 48 bitop3:0x78
	v_or_b32_e32 v81, v0, v1
	v_bitop3_b32 v82, v0, 64, v1 bitop3:0x36
	v_lshlrev_b32_e32 v0, 6, v2
	v_and_b32_e32 v83, 0xffffe000, v0
	v_lshlrev_b32_e32 v0, 13, v3
	v_and_b32_e32 v0, 0x2000, v0
	v_or_b32_e32 v84, 0x4000, v0
	v_mov_b32_e32 v0, 0
	s_mov_b32 s1, 64
	s_mov_b32 s28, 0
	v_mov_b32_e32 v1, v0
	v_mov_b32_e32 v2, v0
	v_mov_b32_e32 v3, v0
	v_mov_b32_e32 v4, v0
	v_mov_b32_e32 v5, v0
	v_mov_b32_e32 v6, v0
	v_mov_b32_e32 v7, v0
	v_mov_b32_e32 v8, v0
	v_mov_b32_e32 v9, v0
	v_mov_b32_e32 v10, v0
	v_mov_b32_e32 v11, v0
	v_mov_b32_e32 v12, v0
	v_mov_b32_e32 v13, v0
	v_mov_b32_e32 v14, v0
	v_mov_b32_e32 v15, v0
	v_mov_b32_e32 v16, v0
	v_mov_b32_e32 v17, v0
	v_mov_b32_e32 v18, v0
	v_mov_b32_e32 v19, v0
	v_mov_b32_e32 v20, v0
	v_mov_b32_e32 v21, v0
	v_mov_b32_e32 v22, v0
	v_mov_b32_e32 v23, v0
	v_mov_b32_e32 v24, v0
	v_mov_b32_e32 v25, v0
	v_mov_b32_e32 v26, v0
	v_mov_b32_e32 v27, v0
	v_mov_b32_e32 v28, v0
	v_mov_b32_e32 v29, v0
	v_mov_b32_e32 v30, v0
	v_mov_b32_e32 v31, v0
	v_mov_b32_e32 v32, v0
	v_mov_b32_e32 v33, v0
	v_mov_b32_e32 v34, v0
	v_mov_b32_e32 v35, v0
	v_mov_b32_e32 v36, v0
	v_mov_b32_e32 v37, v0
	v_mov_b32_e32 v38, v0
	v_mov_b32_e32 v39, v0
	v_mov_b32_e32 v40, v0
	v_mov_b32_e32 v41, v0
	v_mov_b32_e32 v42, v0
	v_mov_b32_e32 v43, v0
	v_mov_b32_e32 v44, v0
	v_mov_b32_e32 v45, v0
	v_mov_b32_e32 v46, v0
	v_mov_b32_e32 v47, v0
	v_mov_b32_e32 v48, v0
	v_mov_b32_e32 v49, v0
	v_mov_b32_e32 v50, v0
	v_mov_b32_e32 v51, v0
	v_mov_b32_e32 v52, v0
	v_mov_b32_e32 v53, v0
	v_mov_b32_e32 v54, v0
	v_mov_b32_e32 v55, v0
	v_mov_b32_e32 v56, v0
	v_mov_b32_e32 v57, v0
	v_mov_b32_e32 v58, v0
	v_mov_b32_e32 v59, v0
	v_mov_b32_e32 v60, v0
	v_mov_b32_e32 v61, v0
	v_mov_b32_e32 v62, v0
	v_mov_b32_e32 v63, v0
	s_movk_i32 s36, 0x80
	s_mov_b32 s37, 0
	v_add_u32_e32 v85, 0x8000, v80
	s_nop 1
	v_readfirstlane_b32 s31, v85
	v_add_u32_e32 v88, 0x400, v85
	v_lshl_add_u64 v[86:87], v[64:65], 0, s[36:37]
	s_mov_b32 m0, s31
	v_readfirstlane_b32 s31, v88
	v_add_u32_e32 v88, 0x800, v85
	global_load_lds_dwordx4 v[86:87], off
	v_lshl_add_u64 v[86:87], v[68:69], 0, s[36:37]
	s_mov_b32 m0, s31
	v_readfirstlane_b32 s31, v88
	v_add_u32_e32 v88, 0xc00, v85
	global_load_lds_dwordx4 v[86:87], off
	v_lshl_add_u64 v[86:87], v[70:71], 0, s[36:37]
	s_mov_b32 m0, s31
	v_readfirstlane_b32 s31, v88
	v_add_u32_e32 v88, 0x4000, v85
	global_load_lds_dwordx4 v[86:87], off
	v_lshl_add_u64 v[86:87], v[72:73], 0, s[36:37]
	s_mov_b32 m0, s31
	v_readfirstlane_b32 s31, v88
	v_add_u32_e32 v88, 0x4400, v85
	global_load_lds_dwordx4 v[86:87], off
	v_lshl_add_u64 v[86:87], v[66:67], 0, s[36:37]
	s_mov_b32 m0, s31
	v_readfirstlane_b32 s31, v88
	v_add_u32_e32 v88, 0x4800, v85
	global_load_lds_dwordx4 v[86:87], off
	v_lshl_add_u64 v[86:87], v[74:75], 0, s[36:37]
	s_mov_b32 m0, s31
	v_readfirstlane_b32 s31, v88
	v_add_u32_e32 v85, 0x4c00, v85
	global_load_lds_dwordx4 v[86:87], off
	v_lshl_add_u64 v[86:87], v[76:77], 0, s[36:37]
	s_mov_b32 m0, s31
	v_readfirstlane_b32 s31, v85
	global_load_lds_dwordx4 v[86:87], off
	v_lshl_add_u64 v[86:87], v[78:79], 0, s[36:37]
	s_mov_b32 m0, s31
	s_nop 0
	global_load_lds_dwordx4 v[86:87], off
.LBB0_252:
	s_cmp_lt_i32 s1, 1024
	s_cbranch_scc1 .LgpB_w8
	s_waitcnt vmcnt(0)
	s_branch .LgpB_wd

.LgpB_wd:
	s_and_b32 s31, s28, 0x8000
	s_waitcnt lgkmcnt(0)
	s_barrier
	v_add_u32_e32 v85, s31, v83
	v_or_b32_e32 v86, s31, v84
	v_add_u32_e32 v126, v85, v81
	v_add_u32_e32 v85, v85, v82
	v_add_u32_e32 v127, v86, v81
	v_add_u32_e32 v128, v86, v82
	ds_read_b128 v[86:89], v126
	ds_read_b128 v[90:93], v126 offset:2048
	ds_read_b128 v[94:97], v126 offset:4096
	ds_read_b128 v[98:101], v126 offset:6144
	ds_read_b128 v[102:105], v127
	ds_read_b128 v[106:109], v127 offset:2048
	ds_read_b128 v[110:113], v127 offset:4096
	ds_read_b128 v[114:117], v127 offset:6144
	ds_read_b128 v[118:121], v85
	ds_read_b128 v[122:125], v85 offset:2048
	ds_read_b128 v[134:137], v85 offset:4096
	ds_read_b128 v[138:141], v85 offset:6144
	ds_read_b128 v[142:145], v128
	ds_read_b128 v[146:149], v128 offset:2048
	ds_read_b128 v[150:153], v128 offset:4096
	ds_read_b128 v[154:157], v128 offset:6144
	s_waitcnt lgkmcnt(8)
	v_mfma_f32_16x16x32_bf16 v[60:63], v[102:105], v[86:89], v[60:63]
	v_mfma_f32_16x16x32_bf16 v[56:59], v[106:109], v[86:89], v[56:59]
	v_mfma_f32_16x16x32_bf16 v[52:55], v[110:113], v[86:89], v[52:55]
	v_mfma_f32_16x16x32_bf16 v[48:51], v[114:117], v[86:89], v[48:51]
	v_mfma_f32_16x16x32_bf16 v[44:47], v[102:105], v[90:93], v[44:47]
	v_mfma_f32_16x16x32_bf16 v[40:43], v[106:109], v[90:93], v[40:43]
	v_mfma_f32_16x16x32_bf16 v[36:39], v[110:113], v[90:93], v[36:39]
	v_mfma_f32_16x16x32_bf16 v[32:35], v[114:117], v[90:93], v[32:35]
	v_mfma_f32_16x16x32_bf16 v[28:31], v[102:105], v[94:97], v[28:31]
	v_mfma_f32_16x16x32_bf16 v[24:27], v[106:109], v[94:97], v[24:27]
	v_mfma_f32_16x16x32_bf16 v[20:23], v[110:113], v[94:97], v[20:23]
	v_mfma_f32_16x16x32_bf16 v[12:15], v[102:105], v[98:101], v[12:15]
	v_mfma_f32_16x16x32_bf16 v[8:11], v[106:109], v[98:101], v[8:11]
	v_mfma_f32_16x16x32_bf16 v[4:7], v[110:113], v[98:101], v[4:7]
	v_mfma_f32_16x16x32_bf16 v[0:3], v[114:117], v[98:101], v[0:3]
	v_mfma_f32_16x16x32_bf16 v[16:19], v[114:117], v[94:97], v[16:19]
	s_waitcnt lgkmcnt(0)
	s_barrier
	s_add_i32 s36, s1, 64
	s_cmp_ge_i32 s36, 1024
	s_cbranch_scc1 .LgpB_nd
	v_add_u32_e32 v85, s31, v80
	s_ashr_i32 s37, s36, 31
	s_lshl_b64 s[36:37], s[36:37], 1
	v_readfirstlane_b32 s31, v85
	v_add_u32_e32 v88, 0x400, v85
	v_lshl_add_u64 v[86:87], v[64:65], 0, s[36:37]
	s_mov_b32 m0, s31
	v_readfirstlane_b32 s31, v88
	v_add_u32_e32 v88, 0x800, v85
	global_load_lds_dwordx4 v[86:87], off
	v_lshl_add_u64 v[86:87], v[68:69], 0, s[36:37]
	s_mov_b32 m0, s31
	v_readfirstlane_b32 s31, v88
	v_add_u32_e32 v88, 0xc00, v85
	global_load_lds_dwordx4 v[86:87], off
	v_lshl_add_u64 v[86:87], v[70:71], 0, s[36:37]
	s_mov_b32 m0, s31
	v_readfirstlane_b32 s31, v88
	v_add_u32_e32 v88, 0x4000, v85
	global_load_lds_dwordx4 v[86:87], off
	v_lshl_add_u64 v[86:87], v[72:73], 0, s[36:37]
	s_mov_b32 m0, s31
	v_readfirstlane_b32 s31, v88
	v_add_u32_e32 v88, 0x4400, v85
	global_load_lds_dwordx4 v[86:87], off
	v_lshl_add_u64 v[86:87], v[66:67], 0, s[36:37]
	s_mov_b32 m0, s31
	v_readfirstlane_b32 s31, v88
	v_add_u32_e32 v88, 0x4800, v85
	global_load_lds_dwordx4 v[86:87], off
	v_lshl_add_u64 v[86:87], v[74:75], 0, s[36:37]
	s_mov_b32 m0, s31
	v_readfirstlane_b32 s31, v88
	v_add_u32_e32 v85, 0x4c00, v85
	global_load_lds_dwordx4 v[86:87], off
	v_lshl_add_u64 v[86:87], v[76:77], 0, s[36:37]
	s_mov_b32 m0, s31
	v_readfirstlane_b32 s31, v85
	global_load_lds_dwordx4 v[86:87], off
	v_lshl_add_u64 v[86:87], v[78:79], 0, s[36:37]
	s_mov_b32 m0, s31
	s_nop 0
	global_load_lds_dwordx4 v[86:87], off
.LgpB_nd:
	s_nop 0
	v_mfma_f32_16x16x32_bf16 v[60:63], v[142:145], v[118:121], v[60:63]
	v_mfma_f32_16x16x32_bf16 v[56:59], v[146:149], v[118:121], v[56:59]
	v_mfma_f32_16x16x32_bf16 v[52:55], v[150:153], v[118:121], v[52:55]
	v_mfma_f32_16x16x32_bf16 v[48:51], v[154:157], v[118:121], v[48:51]
	v_mfma_f32_16x16x32_bf16 v[44:47], v[142:145], v[122:125], v[44:47]
	v_mfma_f32_16x16x32_bf16 v[40:43], v[146:149], v[122:125], v[40:43]
	v_mfma_f32_16x16x32_bf16 v[36:39], v[150:153], v[122:125], v[36:39]
	v_mfma_f32_16x16x32_bf16 v[32:35], v[154:157], v[122:125], v[32:35]
	v_mfma_f32_16x16x32_bf16 v[28:31], v[142:145], v[134:137], v[28:31]
	v_mfma_f32_16x16x32_bf16 v[24:27], v[146:149], v[134:137], v[24:27]
	v_mfma_f32_16x16x32_bf16 v[20:23], v[150:153], v[134:137], v[20:23]
	v_mfma_f32_16x16x32_bf16 v[16:19], v[154:157], v[134:137], v[16:19]
	v_mfma_f32_16x16x32_bf16 v[12:15], v[142:145], v[138:141], v[12:15]
	v_mfma_f32_16x16x32_bf16 v[8:11], v[146:149], v[138:141], v[8:11]
	v_mfma_f32_16x16x32_bf16 v[4:7], v[150:153], v[138:141], v[4:7]
	v_mfma_f32_16x16x32_bf16 v[0:3], v[154:157], v[138:141], v[0:3]
	s_add_i32 s1, s1, 64
	s_add_i32 s28, s28, 0x8000
	s_cmp_lg_u32 s28, 0x80000
	s_cbranch_scc1 .LBB0_252
	s_waitcnt vmcnt(0)
	v_mov_b32_e32 v64, v208
	s_waitcnt lgkmcnt(0)
	s_barrier
	v_mov_b32_e32 v65, v208
	v_and_b32_e32 v67, 15, v64
	v_lshrrev_b32_e32 v64, 1, v64
	v_and_b32_e32 v64, 24, v64
	v_ashrrev_i32_e32 v66, 1, v65
	s_movk_i32 s1, 0xffc0
	v_and_or_b32 v64, v65, 64, v64
	v_and_or_b32 v65, v66, s1, v67
	v_lshl_add_u32 v65, s30, 7, v65
	s_lshl_b32 s0, s0, 7
	v_cvt_pk_bf16_f32 v60, v60, v61
	v_cvt_pk_bf16_f32 v61, v62, v63
	v_cvt_pk_bf16_f32 v62, v56, v57
	v_mov_b64_e32 v[56:57], s[70:71]
	s_ashr_i32 s1, s0, 31
	v_cvt_pk_bf16_f32 v44, v44, v45
	v_cvt_pk_bf16_f32 v45, v46, v47
	v_cvt_pk_bf16_f32 v46, v40, v41
	v_or_b32_e32 v40, 16, v65
	v_cvt_pk_bf16_f32 v28, v28, v29
	v_cvt_pk_bf16_f32 v29, v30, v31
	v_cvt_pk_bf16_f32 v30, v24, v25
	v_or_b32_e32 v24, 32, v65
	v_cvt_pk_bf16_f32 v12, v12, v13
	v_cvt_pk_bf16_f32 v13, v14, v15
	v_cvt_pk_bf16_f32 v14, v8, v9
	v_or_b32_e32 v8, 48, v65
	v_cvt_pk_bf16_f32 v63, v58, v59
	v_mad_i64_i32 v[58:59], s[30:31], v65, s40, v[56:57]
	s_lshl_b64 s[0:1], s[0:1], 1
	v_mad_i64_i32 v[40:41], s[30:31], v40, s40, v[56:57]
	v_mad_i64_i32 v[24:25], s[30:31], v24, s40, v[56:57]
	v_mad_i64_i32 v[8:9], s[30:31], v8, s40, v[56:57]
	v_lshl_add_u64 v[58:59], v[58:59], 0, s[0:1]
	v_lshlrev_b32_e32 v128, 1, v64
	v_lshl_add_u64 v[40:41], v[40:41], 0, s[0:1]
	v_lshl_add_u64 v[24:25], v[24:25], 0, s[0:1]
	v_lshl_add_u64 v[8:9], v[8:9], 0, s[0:1]
	s_add_i32 s27, s27, s22
	v_lshl_add_u64 v[58:59], v[58:59], 0, v[128:129]
	v_cvt_pk_bf16_f32 v52, v52, v53
	v_cvt_pk_bf16_f32 v53, v54, v55
	v_cvt_pk_bf16_f32 v54, v48, v49
	v_cvt_pk_bf16_f32 v55, v50, v51
	v_cvt_pk_bf16_f32 v47, v42, v43
	v_lshl_add_u64 v[40:41], v[40:41], 0, v[128:129]
	v_cvt_pk_bf16_f32 v36, v36, v37
	v_cvt_pk_bf16_f32 v37, v38, v39
	v_cvt_pk_bf16_f32 v38, v32, v33
	v_cvt_pk_bf16_f32 v39, v34, v35
	v_cvt_pk_bf16_f32 v31, v26, v27
	v_lshl_add_u64 v[24:25], v[24:25], 0, v[128:129]
	v_cvt_pk_bf16_f32 v20, v20, v21
	v_cvt_pk_bf16_f32 v21, v22, v23
	v_cvt_pk_bf16_f32 v22, v16, v17
	v_cvt_pk_bf16_f32 v23, v18, v19
	v_cvt_pk_bf16_f32 v15, v10, v11
	v_lshl_add_u64 v[8:9], v[8:9], 0, v[128:129]
	v_cvt_pk_bf16_f32 v4, v4, v5
	v_cvt_pk_bf16_f32 v5, v6, v7
	v_cvt_pk_bf16_f32 v6, v0, v1
	v_cvt_pk_bf16_f32 v7, v2, v3
	s_cmpk_gt_i32 s27, 0x7f7
	global_store_dwordx4 v[58:59], v[60:63], off
	global_store_dwordx4 v[58:59], v[52:55], off offset:64
	global_store_dwordx4 v[40:41], v[44:47], off
	global_store_dwordx4 v[40:41], v[36:39], off offset:64
	global_store_dwordx4 v[24:25], v[28:31], off
	global_store_dwordx4 v[24:25], v[20:23], off offset:64
	global_store_dwordx4 v[8:9], v[12:15], off
	global_store_dwordx4 v[8:9], v[4:7], off offset:64
	s_cbranch_scc0 .LBB0_251
